# baseline (speedup 1.0000x reference)
; DI unsigned pk_bf16(float lo, float hi) { f32x2_t v = {lo, hi}; return __builtin_bit_cast(unsigned, __builtin_convertvector(v, bf16x2_t)); }
; DI float fsigmoid(float x) { return __builtin_amdgcn_rcpf(1.0f + __expf(-x)); }
; #define EPI_M _Pragma("unroll") for (int m = 0; m < 8; ++m)
; #define EPI_N _Pragma("unroll") for (int n = 0; n < 4; ++n)
; DI void p5_phase(const Params& p, char* lds) {
;     ...
;     EPI_IDX_N
;     EPI_M {
;       EPI_N {
;         u32x2 o; o[0] = pk_bf16(fsigmoid(ACC(m, n)[0]), fsigmoid(ACC(m, n)[1])); o[1] = pk_bf16(fsigmoid(ACC(m, n)[2]), fsigmoid(ACC(m, n)[3]));
;         tg[(m * 4 + n) * 512 + tid] = o;
;       }
;       __builtin_amdgcn_sched_barrier(0);
.LBB0_976:
	s_or_b64 exec, exec, s[22:23]
	s_waitcnt vmcnt(0)
	s_barrier
	s_getreg_b32 s7, hwreg(HW_REG_HW_ID, 0, 6)
	s_lshl_b32 s7, s7, 2
	s_and_b32 s7, s7, 0xfc
	s_add_i32 s7, s7, 0x20040
	v_mov_b32_e32 v64, s7
	ds_read_b32 v64, v64
	v_mul_f32_e32 v126, 0xbfb8aa3b, v126
	v_mul_f32_e32 v127, 0xbfb8aa3b, v127
	v_exp_f32_e32 v126, v126
	v_exp_f32_e32 v127, v127
	s_waitcnt lgkmcnt(0)
	v_readfirstlane_b32 s7, v64
	v_add_f32_e32 v64, 1.0, v126
	v_add_f32_e32 v126, 1.0, v127
	v_mul_f32_e32 v127, 0xbfb8aa3b, v128
	v_exp_f32_e32 v127, v127
	v_mul_f32_e32 v128, 0xbfb8aa3b, v129
	v_rcp_f32_e32 v64, v64
	v_exp_f32_e32 v128, v128
	v_rcp_f32_e32 v129, v126
	v_add_f32_e32 v126, 1.0, v127
	v_rcp_f32_e32 v127, v126
	v_add_f32_e32 v126, 1.0, v128
	v_cvt_pk_bf16_f32 v128, v64, v129
	v_mul_f32_e32 v64, 0xbfb8aa3b, v122
	v_mul_f32_e32 v122, 0xbfb8aa3b, v123
	v_exp_f32_e32 v64, v64
	v_exp_f32_e32 v122, v122
	v_mul_f32_e32 v123, 0xbfb8aa3b, v124
	v_exp_f32_e32 v123, v123
	v_mul_f32_e32 v124, 0xbfb8aa3b, v125
	v_rcp_f32_e32 v130, v126
	v_exp_f32_e32 v124, v124
	v_add_f32_e32 v64, 1.0, v64
	v_add_f32_e32 v122, 1.0, v122
	v_rcp_f32_e32 v64, v64
	v_rcp_f32_e32 v125, v122
	v_lshl_or_b32 v126, s7, 6, v214
	v_add_f32_e32 v122, 1.0, v123
	v_cvt_pk_bf16_f32 v129, v127, v130
	v_ashrrev_i32_e32 v127, 31, v126
	v_rcp_f32_e32 v130, v122
	v_add_f32_e32 v122, 1.0, v124
	v_rcp_f32_e32 v124, v122
	v_lshl_add_u64 v[122:123], v[126:127], 3, s[10:11]
	global_store_dwordx2 v[122:123], v[128:129], off sc0 sc1
	v_cvt_pk_bf16_f32 v122, v64, v125
	v_mul_f32_e32 v64, 0xbfb8aa3b, v118
	v_mul_f32_e32 v118, 0xbfb8aa3b, v119
	v_exp_f32_e32 v64, v64
	v_exp_f32_e32 v118, v118
	v_mul_f32_e32 v119, 0xbfb8aa3b, v120
	v_exp_f32_e32 v119, v119
	v_mul_f32_e32 v120, 0xbfb8aa3b, v121
	v_exp_f32_e32 v120, v120
	v_add_f32_e32 v64, 1.0, v64
	v_add_f32_e32 v118, 1.0, v118
	v_rcp_f32_e32 v64, v64
	v_rcp_f32_e32 v121, v118
	v_cvt_pk_bf16_f32 v123, v130, v124
	v_add_u32_e32 v124, 0x200, v126
	v_add_f32_e32 v118, 1.0, v119
	v_ashrrev_i32_e32 v125, 31, v124
	v_rcp_f32_e32 v127, v118
	v_add_f32_e32 v118, 1.0, v120
	v_rcp_f32_e32 v120, v118
	v_lshl_add_u64 v[118:119], v[124:125], 3, s[10:11]
	global_store_dwordx2 v[118:119], v[122:123], off sc0 sc1
	v_cvt_pk_bf16_f32 v118, v64, v121
	v_mul_f32_e32 v64, 0xbfb8aa3b, v114
	v_mul_f32_e32 v114, 0xbfb8aa3b, v115
	v_exp_f32_e32 v114, v114
	v_mul_f32_e32 v115, 0xbfb8aa3b, v116
	v_exp_f32_e32 v115, v115
	v_mul_f32_e32 v116, 0xbfb8aa3b, v117
	v_exp_f32_e32 v116, v116
	v_exp_f32_e32 v64, v64
	v_add_f32_e32 v114, 1.0, v114
	v_rcp_f32_e32 v117, v114
	v_add_f32_e32 v114, 1.0, v115
	v_rcp_f32_e32 v122, v114
	v_add_f32_e32 v114, 1.0, v116
	v_add_f32_e32 v64, 1.0, v64
	v_rcp_f32_e32 v116, v114
	v_cvt_pk_bf16_f32 v119, v127, v120
	v_add_u32_e32 v120, 0x400, v126
	v_rcp_f32_e32 v64, v64
	v_ashrrev_i32_e32 v121, 31, v120
	v_lshl_add_u64 v[114:115], v[120:121], 3, s[10:11]
	global_store_dwordx2 v[114:115], v[118:119], off sc0 sc1
	v_cvt_pk_bf16_f32 v115, v122, v116
	v_add_u32_e32 v116, 0x600, v126
	v_cvt_pk_bf16_f32 v114, v64, v117
	v_ashrrev_i32_e32 v117, 31, v116
	v_lshl_add_u64 v[116:117], v[116:117], 3, s[10:11]
	global_store_dwordx2 v[116:117], v[114:115], off sc0 sc1
	v_mul_f32_e32 v64, 0xbfb8aa3b, v110
	v_mul_f32_e32 v110, 0xbfb8aa3b, v111
	v_exp_f32_e32 v64, v64
	v_exp_f32_e32 v110, v110
	v_mul_f32_e32 v111, 0xbfb8aa3b, v112
	v_exp_f32_e32 v111, v111
	v_add_f32_e32 v64, 1.0, v64
	v_add_f32_e32 v110, 1.0, v110
	v_mul_f32_e32 v112, 0xbfb8aa3b, v113
	v_rcp_f32_e32 v64, v64
	v_exp_f32_e32 v112, v112
	v_rcp_f32_e32 v113, v110
	v_add_f32_e32 v110, 1.0, v111
	v_rcp_f32_e32 v111, v110
	v_add_f32_e32 v110, 1.0, v112
	v_cvt_pk_bf16_f32 v112, v64, v113
	v_mul_f32_e32 v64, 0xbfb8aa3b, v106
	v_mul_f32_e32 v106, 0xbfb8aa3b, v107
	v_exp_f32_e32 v64, v64
	v_exp_f32_e32 v106, v106
	v_mul_f32_e32 v107, 0xbfb8aa3b, v108
	v_exp_f32_e32 v107, v107
	v_mul_f32_e32 v108, 0xbfb8aa3b, v109
	v_rcp_f32_e32 v114, v110
	v_exp_f32_e32 v108, v108
	v_add_f32_e32 v64, 1.0, v64
	v_add_f32_e32 v106, 1.0, v106
	v_rcp_f32_e32 v64, v64
	v_rcp_f32_e32 v109, v106
	v_add_u32_e32 v110, 0x800, v126
	v_add_f32_e32 v106, 1.0, v107
	v_cvt_pk_bf16_f32 v113, v111, v114
	v_ashrrev_i32_e32 v111, 31, v110
	v_rcp_f32_e32 v114, v106
	v_add_f32_e32 v106, 1.0, v108
	v_rcp_f32_e32 v108, v106
	v_lshl_add_u64 v[106:107], v[110:111], 3, s[10:11]
	global_store_dwordx2 v[106:107], v[112:113], off sc0 sc1
	v_cvt_pk_bf16_f32 v106, v64, v109
	v_mul_f32_e32 v64, 0xbfb8aa3b, v102
	v_mul_f32_e32 v102, 0xbfb8aa3b, v103
	v_exp_f32_e32 v64, v64
	v_exp_f32_e32 v102, v102
	v_mul_f32_e32 v103, 0xbfb8aa3b, v104
	v_exp_f32_e32 v103, v103
	v_mul_f32_e32 v104, 0xbfb8aa3b, v105
	v_exp_f32_e32 v104, v104
	v_add_f32_e32 v64, 1.0, v64
	v_add_f32_e32 v102, 1.0, v102
	v_rcp_f32_e32 v64, v64
	v_rcp_f32_e32 v105, v102
	v_cvt_pk_bf16_f32 v107, v114, v108
	v_add_u32_e32 v108, 0xa00, v126
	v_add_f32_e32 v102, 1.0, v103
	v_ashrrev_i32_e32 v109, 31, v108
	v_rcp_f32_e32 v110, v102
	v_add_f32_e32 v102, 1.0, v104
	v_rcp_f32_e32 v104, v102
	v_lshl_add_u64 v[102:103], v[108:109], 3, s[10:11]
	global_store_dwordx2 v[102:103], v[106:107], off sc0 sc1
	v_cvt_pk_bf16_f32 v102, v64, v105
	v_mul_f32_e32 v64, 0xbfb8aa3b, v98
	v_mul_f32_e32 v98, 0xbfb8aa3b, v99
	v_exp_f32_e32 v98, v98
	v_mul_f32_e32 v99, 0xbfb8aa3b, v100
	v_exp_f32_e32 v99, v99
	v_mul_f32_e32 v100, 0xbfb8aa3b, v101
	v_exp_f32_e32 v100, v100
	v_exp_f32_e32 v64, v64
	v_add_f32_e32 v98, 1.0, v98
	v_rcp_f32_e32 v101, v98
	v_add_f32_e32 v98, 1.0, v99
	v_rcp_f32_e32 v106, v98
	v_add_f32_e32 v98, 1.0, v100
	v_add_f32_e32 v64, 1.0, v64
	v_rcp_f32_e32 v100, v98
	v_cvt_pk_bf16_f32 v103, v110, v104
; DI unsigned pk_bf16(float lo, float hi) { f32x2_t v = {lo, hi}; return __builtin_bit_cast(unsigned, __builtin_convertvector(v, bf16x2_t)); }
; DI float fsigmoid(float x) { return __builtin_amdgcn_rcpf(1.0f + __expf(-x)); }
; #define EPI_M _Pragma("unroll") for (int m = 0; m < 8; ++m)
; #define EPI_N _Pragma("unroll") for (int n = 0; n < 4; ++n)
; DI void p5_phase(const Params& p, char* lds) {
;     ...
;     EPI_M {
;       EPI_N {
;         u32x2 o; o[0] = pk_bf16(fsigmoid(ACC(m, n)[0]), fsigmoid(ACC(m, n)[1])); o[1] = pk_bf16(fsigmoid(ACC(m, n)[2]), fsigmoid(ACC(m, n)[3]));
;         tg[(m * 4 + n) * 512 + tid] = o;
;       }
;       __builtin_amdgcn_sched_barrier(0);
;     }
	v_add_u32_e32 v104, 0xc00, v126
	v_rcp_f32_e32 v64, v64
	v_ashrrev_i32_e32 v105, 31, v104
	v_lshl_add_u64 v[98:99], v[104:105], 3, s[10:11]
	global_store_dwordx2 v[98:99], v[102:103], off sc0 sc1
	v_cvt_pk_bf16_f32 v99, v106, v100
	v_add_u32_e32 v100, 0xe00, v126
	v_cvt_pk_bf16_f32 v98, v64, v101
	v_ashrrev_i32_e32 v101, 31, v100
	v_lshl_add_u64 v[100:101], v[100:101], 3, s[10:11]
	global_store_dwordx2 v[100:101], v[98:99], off sc0 sc1
	v_mul_f32_e32 v64, 0xbfb8aa3b, v94
	v_mul_f32_e32 v94, 0xbfb8aa3b, v95
	v_exp_f32_e32 v64, v64
	v_exp_f32_e32 v94, v94
	v_mul_f32_e32 v95, 0xbfb8aa3b, v96
	v_exp_f32_e32 v95, v95
	v_add_f32_e32 v64, 1.0, v64
	v_add_f32_e32 v94, 1.0, v94
	v_mul_f32_e32 v96, 0xbfb8aa3b, v97
	v_rcp_f32_e32 v64, v64
	v_exp_f32_e32 v96, v96
	v_rcp_f32_e32 v97, v94
	v_add_f32_e32 v94, 1.0, v95
	v_rcp_f32_e32 v95, v94
	v_add_f32_e32 v94, 1.0, v96
	v_cvt_pk_bf16_f32 v96, v64, v97
	v_mul_f32_e32 v64, 0xbfb8aa3b, v90
	v_mul_f32_e32 v90, 0xbfb8aa3b, v91
	v_exp_f32_e32 v64, v64
	v_exp_f32_e32 v90, v90
	v_mul_f32_e32 v91, 0xbfb8aa3b, v92
	v_exp_f32_e32 v91, v91
	v_mul_f32_e32 v92, 0xbfb8aa3b, v93
	v_rcp_f32_e32 v98, v94
	v_exp_f32_e32 v92, v92
	v_add_f32_e32 v64, 1.0, v64
	v_add_f32_e32 v90, 1.0, v90
	v_rcp_f32_e32 v64, v64
	v_rcp_f32_e32 v93, v90
	v_add_u32_e32 v94, 0x1000, v126
	v_add_f32_e32 v90, 1.0, v91
	v_cvt_pk_bf16_f32 v97, v95, v98
	v_ashrrev_i32_e32 v95, 31, v94
	v_rcp_f32_e32 v98, v90
	v_add_f32_e32 v90, 1.0, v92
	v_rcp_f32_e32 v92, v90
	v_lshl_add_u64 v[90:91], v[94:95], 3, s[10:11]
	global_store_dwordx2 v[90:91], v[96:97], off sc0 sc1
	v_cvt_pk_bf16_f32 v90, v64, v93
	v_mul_f32_e32 v64, 0xbfb8aa3b, v86
	v_mul_f32_e32 v86, 0xbfb8aa3b, v87
	v_exp_f32_e32 v64, v64
	v_exp_f32_e32 v86, v86
	v_mul_f32_e32 v87, 0xbfb8aa3b, v88
	v_exp_f32_e32 v87, v87
	v_mul_f32_e32 v88, 0xbfb8aa3b, v89
	v_exp_f32_e32 v88, v88
	v_add_f32_e32 v64, 1.0, v64
	v_add_f32_e32 v86, 1.0, v86
	v_rcp_f32_e32 v64, v64
	v_rcp_f32_e32 v89, v86
	v_cvt_pk_bf16_f32 v91, v98, v92
	v_add_u32_e32 v92, 0x1200, v126
	v_add_f32_e32 v86, 1.0, v87
	v_ashrrev_i32_e32 v93, 31, v92
	v_rcp_f32_e32 v94, v86
	v_add_f32_e32 v86, 1.0, v88
	v_rcp_f32_e32 v88, v86
	v_lshl_add_u64 v[86:87], v[92:93], 3, s[10:11]
	global_store_dwordx2 v[86:87], v[90:91], off sc0 sc1
	v_cvt_pk_bf16_f32 v86, v64, v89
	v_mul_f32_e32 v64, 0xbfb8aa3b, v82
	v_mul_f32_e32 v82, 0xbfb8aa3b, v83
	v_exp_f32_e32 v82, v82
	v_mul_f32_e32 v83, 0xbfb8aa3b, v84
	v_exp_f32_e32 v83, v83
	v_mul_f32_e32 v84, 0xbfb8aa3b, v85
	v_exp_f32_e32 v84, v84
	v_exp_f32_e32 v64, v64
	v_add_f32_e32 v82, 1.0, v82
	v_rcp_f32_e32 v85, v82
	v_add_f32_e32 v82, 1.0, v83
	v_rcp_f32_e32 v90, v82
	v_add_f32_e32 v82, 1.0, v84
	v_add_f32_e32 v64, 1.0, v64
	v_rcp_f32_e32 v84, v82
	v_cvt_pk_bf16_f32 v87, v94, v88
	v_add_u32_e32 v88, 0x1400, v126
	v_rcp_f32_e32 v64, v64
	v_ashrrev_i32_e32 v89, 31, v88
	v_lshl_add_u64 v[82:83], v[88:89], 3, s[10:11]
	global_store_dwordx2 v[82:83], v[86:87], off sc0 sc1
	v_cvt_pk_bf16_f32 v83, v90, v84
	v_add_u32_e32 v84, 0x1600, v126
	v_cvt_pk_bf16_f32 v82, v64, v85
	v_ashrrev_i32_e32 v85, 31, v84
	v_lshl_add_u64 v[84:85], v[84:85], 3, s[10:11]
	global_store_dwordx2 v[84:85], v[82:83], off sc0 sc1
	v_mul_f32_e32 v64, 0xbfb8aa3b, v78
	v_mul_f32_e32 v78, 0xbfb8aa3b, v79
	v_exp_f32_e32 v64, v64
	v_exp_f32_e32 v78, v78
	v_mul_f32_e32 v79, 0xbfb8aa3b, v80
	v_exp_f32_e32 v79, v79
	v_add_f32_e32 v64, 1.0, v64
	v_add_f32_e32 v78, 1.0, v78
	v_mul_f32_e32 v80, 0xbfb8aa3b, v81
	v_rcp_f32_e32 v64, v64
	v_exp_f32_e32 v80, v80
	v_rcp_f32_e32 v81, v78
	v_add_f32_e32 v78, 1.0, v79
	v_rcp_f32_e32 v79, v78
	v_add_f32_e32 v78, 1.0, v80
	v_cvt_pk_bf16_f32 v80, v64, v81
	v_mul_f32_e32 v64, 0xbfb8aa3b, v74
	v_mul_f32_e32 v74, 0xbfb8aa3b, v75
	v_exp_f32_e32 v64, v64
	v_exp_f32_e32 v74, v74
	v_mul_f32_e32 v75, 0xbfb8aa3b, v76
	v_exp_f32_e32 v75, v75
	v_mul_f32_e32 v76, 0xbfb8aa3b, v77
	v_rcp_f32_e32 v82, v78
	v_exp_f32_e32 v76, v76
	v_add_f32_e32 v64, 1.0, v64
	v_add_f32_e32 v74, 1.0, v74
	v_rcp_f32_e32 v64, v64
	v_rcp_f32_e32 v77, v74
	v_add_u32_e32 v78, 0x1800, v126
	v_add_f32_e32 v74, 1.0, v75
	v_cvt_pk_bf16_f32 v81, v79, v82
	v_ashrrev_i32_e32 v79, 31, v78
	v_rcp_f32_e32 v82, v74
	v_add_f32_e32 v74, 1.0, v76
	v_rcp_f32_e32 v76, v74
	v_lshl_add_u64 v[74:75], v[78:79], 3, s[10:11]
	global_store_dwordx2 v[74:75], v[80:81], off sc0 sc1
	v_cvt_pk_bf16_f32 v74, v64, v77
	v_mul_f32_e32 v64, 0xbfb8aa3b, v70
	v_mul_f32_e32 v70, 0xbfb8aa3b, v71
	v_exp_f32_e32 v64, v64
	v_exp_f32_e32 v70, v70
	v_mul_f32_e32 v71, 0xbfb8aa3b, v72
	v_exp_f32_e32 v71, v71
	v_mul_f32_e32 v72, 0xbfb8aa3b, v73
	v_exp_f32_e32 v72, v72
	v_add_f32_e32 v64, 1.0, v64
	v_add_f32_e32 v70, 1.0, v70
	v_rcp_f32_e32 v64, v64
	v_rcp_f32_e32 v73, v70
	v_cvt_pk_bf16_f32 v75, v82, v76
	v_add_u32_e32 v76, 0x1a00, v126
	v_add_f32_e32 v70, 1.0, v71
	v_ashrrev_i32_e32 v77, 31, v76
	v_rcp_f32_e32 v78, v70
	v_add_f32_e32 v70, 1.0, v72
	v_rcp_f32_e32 v72, v70
	v_lshl_add_u64 v[70:71], v[76:77], 3, s[10:11]
	global_store_dwordx2 v[70:71], v[74:75], off sc0 sc1
	v_cvt_pk_bf16_f32 v70, v64, v73
	v_mul_f32_e32 v64, 0xbfb8aa3b, v66
	v_mul_f32_e32 v66, 0xbfb8aa3b, v67
	v_exp_f32_e32 v66, v66
	v_mul_f32_e32 v67, 0xbfb8aa3b, v68
	v_exp_f32_e32 v67, v67
	v_mul_f32_e32 v68, 0xbfb8aa3b, v69
	v_exp_f32_e32 v68, v68
	v_exp_f32_e32 v64, v64
	v_add_f32_e32 v66, 1.0, v66
	v_rcp_f32_e32 v69, v66
	v_add_f32_e32 v66, 1.0, v67
	v_rcp_f32_e32 v74, v66
	v_add_f32_e32 v66, 1.0, v68
	v_add_f32_e32 v64, 1.0, v64
	v_rcp_f32_e32 v68, v66
	v_cvt_pk_bf16_f32 v71, v78, v72
	v_add_u32_e32 v72, 0x1c00, v126
	v_rcp_f32_e32 v64, v64
	v_ashrrev_i32_e32 v73, 31, v72
	v_lshl_add_u64 v[66:67], v[72:73], 3, s[10:11]
; DI unsigned pk_bf16(float lo, float hi) { f32x2_t v = {lo, hi}; return __builtin_bit_cast(unsigned, __builtin_convertvector(v, bf16x2_t)); }
; DI float fsigmoid(float x) { return __builtin_amdgcn_rcpf(1.0f + __expf(-x)); }
; #define EPI_M _Pragma("unroll") for (int m = 0; m < 8; ++m)
; #define EPI_N _Pragma("unroll") for (int n = 0; n < 4; ++n)
; DI void p5_phase(const Params& p, char* lds) {
;     ...
;     EPI_M {
;       EPI_N {
;         u32x2 o; o[0] = pk_bf16(fsigmoid(ACC(m, n)[0]), fsigmoid(ACC(m, n)[1])); o[1] = pk_bf16(fsigmoid(ACC(m, n)[2]), fsigmoid(ACC(m, n)[3]));
;         tg[(m * 4 + n) * 512 + tid] = o;
;       }
;       __builtin_amdgcn_sched_barrier(0);
;     }
	global_store_dwordx2 v[66:67], v[70:71], off sc0 sc1
	v_cvt_pk_bf16_f32 v67, v74, v68
	v_add_u32_e32 v68, 0x1e00, v126
	v_cvt_pk_bf16_f32 v66, v64, v69
	v_ashrrev_i32_e32 v69, 31, v68
	v_lshl_add_u64 v[68:69], v[68:69], 3, s[10:11]
	global_store_dwordx2 v[68:69], v[66:67], off sc0 sc1
	v_mul_f32_e32 v60, 0xbfb8aa3b, v60
	v_exp_f32_e32 v60, v60
	v_mul_f32_e32 v61, 0xbfb8aa3b, v61
	v_exp_f32_e32 v61, v61
	v_mul_f32_e32 v56, 0xbfb8aa3b, v56
	v_add_f32_e32 v60, 1.0, v60
	v_rcp_f32_e32 v64, v60
	v_mul_f32_e32 v60, 0xbfb8aa3b, v62
	v_add_f32_e32 v61, 1.0, v61
	v_exp_f32_e32 v60, v60
	v_mul_f32_e32 v62, 0xbfb8aa3b, v63
	v_exp_f32_e32 v56, v56
	v_mul_f32_e32 v57, 0xbfb8aa3b, v57
	v_exp_f32_e32 v62, v62
	v_rcp_f32_e32 v61, v61
	v_exp_f32_e32 v57, v57
	v_add_f32_e32 v60, 1.0, v60
	v_add_f32_e32 v56, 1.0, v56
	v_rcp_f32_e32 v63, v60
	v_add_f32_e32 v60, 1.0, v62
	v_cvt_pk_bf16_f32 v62, v64, v61
	v_rcp_f32_e32 v64, v56
	v_add_f32_e32 v56, 1.0, v57
	v_mul_f32_e32 v57, 0xbfb8aa3b, v58
	v_exp_f32_e32 v57, v57
	v_mul_f32_e32 v58, 0xbfb8aa3b, v59
	v_mul_f32_e32 v52, 0xbfb8aa3b, v52
	v_rcp_f32_e32 v66, v60
	v_exp_f32_e32 v58, v58
	v_exp_f32_e32 v52, v52
	v_mul_f32_e32 v53, 0xbfb8aa3b, v53
	v_exp_f32_e32 v53, v53
	v_add_u32_e32 v60, 0x2000, v126
	v_rcp_f32_e32 v59, v56
	v_add_f32_e32 v56, 1.0, v57
	v_cvt_pk_bf16_f32 v63, v63, v66
	v_ashrrev_i32_e32 v61, 31, v60
	v_rcp_f32_e32 v66, v56
	v_add_f32_e32 v56, 1.0, v58
	v_add_f32_e32 v52, 1.0, v52
	v_rcp_f32_e32 v58, v56
	v_lshl_add_u64 v[56:57], v[60:61], 3, s[10:11]
	v_rcp_f32_e32 v60, v52
	v_add_f32_e32 v52, 1.0, v53
	v_mul_f32_e32 v53, 0xbfb8aa3b, v54
	v_exp_f32_e32 v53, v53
	v_mul_f32_e32 v54, 0xbfb8aa3b, v55
	v_exp_f32_e32 v54, v54
	v_mul_f32_e32 v48, 0xbfb8aa3b, v48
	v_exp_f32_e32 v48, v48
	v_mul_f32_e32 v49, 0xbfb8aa3b, v49
	v_exp_f32_e32 v49, v49
	global_store_dwordx2 v[56:57], v[62:63], off sc0 sc1
	v_cvt_pk_bf16_f32 v57, v66, v58
	v_add_u32_e32 v58, 0x2200, v126
	v_rcp_f32_e32 v55, v52
	v_add_f32_e32 v52, 1.0, v53
	v_cvt_pk_bf16_f32 v56, v64, v59
	v_ashrrev_i32_e32 v59, 31, v58
	v_rcp_f32_e32 v61, v52
	v_add_f32_e32 v52, 1.0, v54
	v_rcp_f32_e32 v54, v52
	v_lshl_add_u64 v[52:53], v[58:59], 3, s[10:11]
	v_add_f32_e32 v48, 1.0, v48
	global_store_dwordx2 v[52:53], v[56:57], off sc0 sc1
	v_rcp_f32_e32 v56, v48
	v_add_f32_e32 v48, 1.0, v49
	v_mul_f32_e32 v49, 0xbfb8aa3b, v50
	v_exp_f32_e32 v49, v49
	v_mul_f32_e32 v50, 0xbfb8aa3b, v51
	v_exp_f32_e32 v50, v50
	v_rcp_f32_e32 v51, v48
	v_add_f32_e32 v48, 1.0, v49
	v_rcp_f32_e32 v57, v48
	v_add_f32_e32 v48, 1.0, v50
	v_rcp_f32_e32 v50, v48
	v_cvt_pk_bf16_f32 v53, v61, v54
	v_add_u32_e32 v54, 0x2400, v126
	v_cvt_pk_bf16_f32 v52, v60, v55
	v_ashrrev_i32_e32 v55, 31, v54
	v_lshl_add_u64 v[48:49], v[54:55], 3, s[10:11]
	global_store_dwordx2 v[48:49], v[52:53], off sc0 sc1
	v_cvt_pk_bf16_f32 v49, v57, v50
	v_add_u32_e32 v50, 0x2600, v126
	v_cvt_pk_bf16_f32 v48, v56, v51
	v_ashrrev_i32_e32 v51, 31, v50
	v_lshl_add_u64 v[50:51], v[50:51], 3, s[10:11]
	global_store_dwordx2 v[50:51], v[48:49], off sc0 sc1
	v_mul_f32_e32 v44, 0xbfb8aa3b, v44
	v_exp_f32_e32 v44, v44
	v_mul_f32_e32 v45, 0xbfb8aa3b, v45
	v_exp_f32_e32 v45, v45
	v_mul_f32_e32 v40, 0xbfb8aa3b, v40
	v_add_f32_e32 v44, 1.0, v44
	v_rcp_f32_e32 v48, v44
	v_mul_f32_e32 v44, 0xbfb8aa3b, v46
	v_add_f32_e32 v45, 1.0, v45
	v_exp_f32_e32 v44, v44
	v_mul_f32_e32 v46, 0xbfb8aa3b, v47
	v_exp_f32_e32 v40, v40
	v_mul_f32_e32 v41, 0xbfb8aa3b, v41
	v_exp_f32_e32 v46, v46
	v_rcp_f32_e32 v45, v45
	v_exp_f32_e32 v41, v41
	v_add_f32_e32 v44, 1.0, v44
	v_add_f32_e32 v40, 1.0, v40
	v_rcp_f32_e32 v47, v44
	v_add_f32_e32 v44, 1.0, v46
	v_cvt_pk_bf16_f32 v46, v48, v45
	v_rcp_f32_e32 v48, v40
	v_add_f32_e32 v40, 1.0, v41
	v_mul_f32_e32 v41, 0xbfb8aa3b, v42
	v_exp_f32_e32 v41, v41
	v_mul_f32_e32 v42, 0xbfb8aa3b, v43
	v_mul_f32_e32 v36, 0xbfb8aa3b, v36
	v_rcp_f32_e32 v49, v44
	v_exp_f32_e32 v42, v42
	v_exp_f32_e32 v36, v36
	v_mul_f32_e32 v37, 0xbfb8aa3b, v37
	v_exp_f32_e32 v37, v37
	v_add_u32_e32 v44, 0x2800, v126
	v_rcp_f32_e32 v43, v40
	v_add_f32_e32 v40, 1.0, v41
	v_cvt_pk_bf16_f32 v47, v47, v49
	v_ashrrev_i32_e32 v45, 31, v44
	v_rcp_f32_e32 v49, v40
	v_add_f32_e32 v40, 1.0, v42
	v_add_f32_e32 v36, 1.0, v36
	v_rcp_f32_e32 v42, v40
	v_lshl_add_u64 v[40:41], v[44:45], 3, s[10:11]
	v_rcp_f32_e32 v44, v36
	v_add_f32_e32 v36, 1.0, v37
	v_mul_f32_e32 v37, 0xbfb8aa3b, v38
	v_exp_f32_e32 v37, v37
	v_mul_f32_e32 v38, 0xbfb8aa3b, v39
	v_exp_f32_e32 v38, v38
	v_mul_f32_e32 v32, 0xbfb8aa3b, v32
	v_exp_f32_e32 v32, v32
	v_mul_f32_e32 v33, 0xbfb8aa3b, v33
	v_exp_f32_e32 v33, v33
	global_store_dwordx2 v[40:41], v[46:47], off sc0 sc1
	v_cvt_pk_bf16_f32 v41, v49, v42
	v_add_u32_e32 v42, 0x2a00, v126
	v_rcp_f32_e32 v39, v36
	v_add_f32_e32 v36, 1.0, v37
	v_cvt_pk_bf16_f32 v40, v48, v43
	v_ashrrev_i32_e32 v43, 31, v42
	v_rcp_f32_e32 v45, v36
	v_add_f32_e32 v36, 1.0, v38
	v_rcp_f32_e32 v38, v36
	v_lshl_add_u64 v[36:37], v[42:43], 3, s[10:11]
	v_add_f32_e32 v32, 1.0, v32
	global_store_dwordx2 v[36:37], v[40:41], off sc0 sc1
	v_rcp_f32_e32 v40, v32
	v_add_f32_e32 v32, 1.0, v33
	v_mul_f32_e32 v33, 0xbfb8aa3b, v34
	v_exp_f32_e32 v33, v33
	v_mul_f32_e32 v34, 0xbfb8aa3b, v35
	v_exp_f32_e32 v34, v34
	v_rcp_f32_e32 v35, v32
	v_add_f32_e32 v32, 1.0, v33
	v_rcp_f32_e32 v41, v32
	v_add_f32_e32 v32, 1.0, v34
	v_rcp_f32_e32 v34, v32
	v_cvt_pk_bf16_f32 v37, v45, v38
	v_add_u32_e32 v38, 0x2c00, v126
	v_cvt_pk_bf16_f32 v36, v44, v39
	v_ashrrev_i32_e32 v39, 31, v38
	v_lshl_add_u64 v[32:33], v[38:39], 3, s[10:11]
	global_store_dwordx2 v[32:33], v[36:37], off sc0 sc1
	v_cvt_pk_bf16_f32 v33, v41, v34
	v_add_u32_e32 v34, 0x2e00, v126
	v_cvt_pk_bf16_f32 v32, v40, v35
; DI unsigned pk_bf16(float lo, float hi) { f32x2_t v = {lo, hi}; return __builtin_bit_cast(unsigned, __builtin_convertvector(v, bf16x2_t)); }
; DI float fsigmoid(float x) { return __builtin_amdgcn_rcpf(1.0f + __expf(-x)); }
; #define EPI_M _Pragma("unroll") for (int m = 0; m < 8; ++m)
; #define EPI_N _Pragma("unroll") for (int n = 0; n < 4; ++n)
; DI void p5_phase(const Params& p, char* lds) {
;     ...
;     EPI_M {
;       EPI_N {
;         u32x2 o; o[0] = pk_bf16(fsigmoid(ACC(m, n)[0]), fsigmoid(ACC(m, n)[1])); o[1] = pk_bf16(fsigmoid(ACC(m, n)[2]), fsigmoid(ACC(m, n)[3]));
;         tg[(m * 4 + n) * 512 + tid] = o;
;       }
;       __builtin_amdgcn_sched_barrier(0);
;     }
;     zero_acc(acc);
;     gemm256(oab + (size_t)row0 * 1024, 1024, (const u16*)(ws + OFF_WA) + (size_t)col0 * 512, (const u16*)(ws + OFF_WA) + (size_t)(col0 + 128) * 512, 512, 8, acc, lds);
	v_ashrrev_i32_e32 v35, 31, v34
	v_lshl_add_u64 v[34:35], v[34:35], 3, s[10:11]
	global_store_dwordx2 v[34:35], v[32:33], off sc0 sc1
	v_mul_f32_e32 v28, 0xbfb8aa3b, v28
	v_exp_f32_e32 v28, v28
	v_mul_f32_e32 v29, 0xbfb8aa3b, v29
	v_exp_f32_e32 v29, v29
	v_mul_f32_e32 v24, 0xbfb8aa3b, v24
	v_add_f32_e32 v28, 1.0, v28
	v_rcp_f32_e32 v32, v28
	v_mul_f32_e32 v28, 0xbfb8aa3b, v30
	v_add_f32_e32 v29, 1.0, v29
	v_exp_f32_e32 v28, v28
	v_mul_f32_e32 v30, 0xbfb8aa3b, v31
	v_exp_f32_e32 v24, v24
	v_mul_f32_e32 v25, 0xbfb8aa3b, v25
	v_exp_f32_e32 v30, v30
	v_rcp_f32_e32 v29, v29
	v_exp_f32_e32 v25, v25
	v_add_f32_e32 v28, 1.0, v28
	v_add_f32_e32 v24, 1.0, v24
	v_rcp_f32_e32 v31, v28
	v_add_f32_e32 v28, 1.0, v30
	v_cvt_pk_bf16_f32 v30, v32, v29
	v_rcp_f32_e32 v32, v24
	v_add_f32_e32 v24, 1.0, v25
	v_mul_f32_e32 v25, 0xbfb8aa3b, v26
	v_exp_f32_e32 v25, v25
	v_mul_f32_e32 v26, 0xbfb8aa3b, v27
	v_mul_f32_e32 v20, 0xbfb8aa3b, v20
	v_rcp_f32_e32 v33, v28
	v_exp_f32_e32 v26, v26
	v_exp_f32_e32 v20, v20
	v_mul_f32_e32 v21, 0xbfb8aa3b, v21
	v_exp_f32_e32 v21, v21
	v_add_u32_e32 v28, 0x3000, v126
	v_rcp_f32_e32 v27, v24
	v_add_f32_e32 v24, 1.0, v25
	v_cvt_pk_bf16_f32 v31, v31, v33
	v_ashrrev_i32_e32 v29, 31, v28
	v_rcp_f32_e32 v33, v24
	v_add_f32_e32 v24, 1.0, v26
	v_add_f32_e32 v20, 1.0, v20
	v_rcp_f32_e32 v26, v24
	v_lshl_add_u64 v[24:25], v[28:29], 3, s[10:11]
	v_rcp_f32_e32 v28, v20
	v_add_f32_e32 v20, 1.0, v21
	v_mul_f32_e32 v21, 0xbfb8aa3b, v22
	v_exp_f32_e32 v21, v21
	v_mul_f32_e32 v22, 0xbfb8aa3b, v23
	v_exp_f32_e32 v22, v22
	v_mul_f32_e32 v16, 0xbfb8aa3b, v16
	v_exp_f32_e32 v16, v16
	v_mul_f32_e32 v17, 0xbfb8aa3b, v17
	v_exp_f32_e32 v17, v17
	global_store_dwordx2 v[24:25], v[30:31], off sc0 sc1
	v_cvt_pk_bf16_f32 v25, v33, v26
	v_add_u32_e32 v26, 0x3200, v126
	v_rcp_f32_e32 v23, v20
	v_add_f32_e32 v20, 1.0, v21
	v_cvt_pk_bf16_f32 v24, v32, v27
	v_ashrrev_i32_e32 v27, 31, v26
	v_rcp_f32_e32 v29, v20
	v_add_f32_e32 v20, 1.0, v22
	v_rcp_f32_e32 v22, v20
	v_lshl_add_u64 v[20:21], v[26:27], 3, s[10:11]
	v_add_f32_e32 v16, 1.0, v16
	global_store_dwordx2 v[20:21], v[24:25], off sc0 sc1
	v_rcp_f32_e32 v24, v16
	v_add_f32_e32 v16, 1.0, v17
	v_mul_f32_e32 v17, 0xbfb8aa3b, v18
	v_exp_f32_e32 v17, v17
	v_mul_f32_e32 v18, 0xbfb8aa3b, v19
	v_exp_f32_e32 v18, v18
	v_rcp_f32_e32 v19, v16
	v_add_f32_e32 v16, 1.0, v17
	v_rcp_f32_e32 v25, v16
	v_add_f32_e32 v16, 1.0, v18
	v_rcp_f32_e32 v18, v16
	v_cvt_pk_bf16_f32 v21, v29, v22
	v_add_u32_e32 v22, 0x3400, v126
	v_cvt_pk_bf16_f32 v20, v28, v23
	v_ashrrev_i32_e32 v23, 31, v22
	v_lshl_add_u64 v[16:17], v[22:23], 3, s[10:11]
	global_store_dwordx2 v[16:17], v[20:21], off sc0 sc1
	v_cvt_pk_bf16_f32 v17, v25, v18
	v_add_u32_e32 v18, 0x3600, v126
	v_cvt_pk_bf16_f32 v16, v24, v19
	v_ashrrev_i32_e32 v19, 31, v18
	v_lshl_add_u64 v[18:19], v[18:19], 3, s[10:11]
	global_store_dwordx2 v[18:19], v[16:17], off sc0 sc1
	v_mul_f32_e32 v12, 0xbfb8aa3b, v12
	v_exp_f32_e32 v12, v12
	v_mul_f32_e32 v13, 0xbfb8aa3b, v13
	v_exp_f32_e32 v13, v13
	v_mul_f32_e32 v8, 0xbfb8aa3b, v8
	v_add_f32_e32 v12, 1.0, v12
	v_rcp_f32_e32 v16, v12
	v_mul_f32_e32 v12, 0xbfb8aa3b, v14
	v_add_f32_e32 v13, 1.0, v13
	v_exp_f32_e32 v12, v12
	v_mul_f32_e32 v14, 0xbfb8aa3b, v15
	v_exp_f32_e32 v8, v8
	v_mul_f32_e32 v9, 0xbfb8aa3b, v9
	v_exp_f32_e32 v14, v14
	v_rcp_f32_e32 v13, v13
	v_exp_f32_e32 v9, v9
	v_add_f32_e32 v12, 1.0, v12
	v_add_f32_e32 v8, 1.0, v8
	v_rcp_f32_e32 v15, v12
	v_add_f32_e32 v12, 1.0, v14
	v_cvt_pk_bf16_f32 v14, v16, v13
	v_rcp_f32_e32 v16, v8
	v_add_f32_e32 v8, 1.0, v9
	v_mul_f32_e32 v9, 0xbfb8aa3b, v10
	v_exp_f32_e32 v9, v9
	v_mul_f32_e32 v10, 0xbfb8aa3b, v11
	v_mul_f32_e32 v4, 0xbfb8aa3b, v4
	v_rcp_f32_e32 v17, v12
	v_exp_f32_e32 v10, v10
	v_exp_f32_e32 v4, v4
	v_mul_f32_e32 v5, 0xbfb8aa3b, v5
	v_exp_f32_e32 v5, v5
	v_add_u32_e32 v12, 0x3800, v126
	v_rcp_f32_e32 v11, v8
	v_add_f32_e32 v8, 1.0, v9
	v_cvt_pk_bf16_f32 v15, v15, v17
	v_ashrrev_i32_e32 v13, 31, v12
	v_rcp_f32_e32 v17, v8
	v_add_f32_e32 v8, 1.0, v10
	v_add_f32_e32 v4, 1.0, v4
	v_rcp_f32_e32 v10, v8
	v_lshl_add_u64 v[8:9], v[12:13], 3, s[10:11]
	v_rcp_f32_e32 v12, v4
	v_add_f32_e32 v4, 1.0, v5
	v_mul_f32_e32 v5, 0xbfb8aa3b, v6
	v_exp_f32_e32 v5, v5
	v_mul_f32_e32 v6, 0xbfb8aa3b, v7
	v_exp_f32_e32 v6, v6
	v_mul_f32_e32 v0, 0xbfb8aa3b, v0
	v_exp_f32_e32 v0, v0
	v_mul_f32_e32 v1, 0xbfb8aa3b, v1
	v_exp_f32_e32 v1, v1
	global_store_dwordx2 v[8:9], v[14:15], off sc0 sc1
	v_cvt_pk_bf16_f32 v9, v17, v10
	v_add_u32_e32 v10, 0x3a00, v126
	v_rcp_f32_e32 v7, v4
	v_add_f32_e32 v4, 1.0, v5
	v_cvt_pk_bf16_f32 v8, v16, v11
	v_ashrrev_i32_e32 v11, 31, v10
	v_rcp_f32_e32 v13, v4
	v_add_f32_e32 v4, 1.0, v6
	v_rcp_f32_e32 v6, v4
	v_lshl_add_u64 v[4:5], v[10:11], 3, s[10:11]
	v_add_f32_e32 v0, 1.0, v0
	global_store_dwordx2 v[4:5], v[8:9], off sc0 sc1
	v_rcp_f32_e32 v8, v0
	v_add_f32_e32 v0, 1.0, v1
	v_mul_f32_e32 v1, 0xbfb8aa3b, v2
	v_exp_f32_e32 v1, v1
	v_mul_f32_e32 v2, 0xbfb8aa3b, v3
	v_exp_f32_e32 v2, v2
	v_rcp_f32_e32 v3, v0
	v_add_f32_e32 v0, 1.0, v1
	v_rcp_f32_e32 v9, v0
	v_add_f32_e32 v0, 1.0, v2
	v_rcp_f32_e32 v2, v0
	v_cvt_pk_bf16_f32 v5, v13, v6
	v_add_u32_e32 v6, 0x3c00, v126
	v_cvt_pk_bf16_f32 v4, v12, v7
	v_ashrrev_i32_e32 v7, 31, v6
	v_lshl_add_u64 v[0:1], v[6:7], 3, s[10:11]
	global_store_dwordx2 v[0:1], v[4:5], off sc0 sc1
	v_cvt_pk_bf16_f32 v1, v9, v2
	v_add_u32_e32 v2, 0x3e00, v126
	v_cvt_pk_bf16_f32 v0, v8, v3
	v_ashrrev_i32_e32 v3, 31, v2
	v_lshl_add_u64 v[2:3], v[2:3], 3, s[10:11]
	global_store_dwordx2 v[2:3], v[0:1], off sc0 sc1
	s_lshl_b64 s[8:9], s[8:9], 1
	v_readlane_b32 s22, v254, 12
	v_readlane_b32 s23, v254, 13
	s_add_u32 s44, s22, s8
	s_addc_u32 s45, s23, s9
	s_lshl_b64 s[48:49], s[38:39], 10
	s_add_u32 s28, s96, s48
	s_addc_u32 s29, s97, s49
	s_or_b32 s8, s38, 0x80
	s_ashr_i32 s9, s8, 31
	s_lshl_b64 s[22:23], s[8:9], 10
	s_add_u32 s22, s96, s22
	s_getreg_b32 s7, hwreg(HW_REG_HW_ID, 0, 6)
	s_addc_u32 s23, s97, s23
	s_lshl_b32 s7, s7, 2
	s_and_b32 s7, s7, 0xfc
	s_add_i32 s7, s7, 0x20040
	v_mov_b32_e32 v0, s7
	ds_read_b32 v0, v0
	v_mov_b32_e32 v131, v65
	s_waitcnt lgkmcnt(0)
; DI int my_tid() { int t = tid_raw(); asm volatile("" : "+v"(t)); return t; }
; #define STAGE_A(b, h, kt) { const u16* ap_ = A + (size_t)((h) * ahalf + (unsigned)(kt) * 64u); glds16(ap_ + ao0, l0 + SA_(b, h)); glds16(ap_ + ao1, l0 + SA_(b, h) + 8192); }
; #define STAGE_B(b, h, kt) { const u16* bp_ = ((h) ? B1 : B0) + (unsigned)(kt) * 64u; glds16(bp_ + bo0, l0 + SB_(b, h)); glds16(bp_ + bo1, l0 + SB_(b, h) + 8192); }
; #define WAIT_V(n) asm volatile("s_waitcnt vmcnt(" #n ")" ::: "memory");
; #define BAR __builtin_amdgcn_s_barrier();
; DI void gemm256(const u16* __restrict__ A, int lda, const u16* __restrict__ B0, const u16* __restrict__ B1, int ldb, int nt, acc_t& acc, char* lds) {
;   const int tid = my_tid();
;   const int lane = tid & 63, wid = tid >> 6, wr = wid >> 2, wc = wid & 3, fr = lane & 15, fq = lane >> 4;
;   int r0, c0, r1, c1;
;   stage_rc(tid * 16, r0, c0); stage_rc(tid * 16 + 8192, r1, c1);
;   const unsigned ao0 = (unsigned)(r0 * lda + c0), ao1 = (unsigned)(r1 * lda + c1);
;   const unsigned ahalf = 128u * (unsigned)lda;
;   const int p0 = (r0 & ~31) + (((r0 & 15) >> 2) * 8) + (((r0 >> 4) & 1) * 4) + (r0 & 3), p1 = (r1 & ~31) + (((r1 & 15) >> 2) * 8) + (((r1 >> 4) & 1) * 4) + (r1 & 3);
;   const unsigned bo0 = (unsigned)(p0 * ldb + c0), bo1 = (unsigned)(p1 * ldb + c1);
;   char* l0 = lds + tid * 16;
;     ...
;   bf16x8 At[4][2], Bq0[2][2], Bq1[2][2];
;   WAIT_V(0)
;   STAGE_B(0, 0, 0) STAGE_A(0, 0, 0) STAGE_B(0, 1, 0) STAGE_A(0, 1, 0)
;   if (wr == 1) BAR
	v_readfirstlane_b32 s7, v0
	s_nop 1
	v_lshl_or_b32 v140, s7, 6, v214
	s_nop 0
	v_bfe_i32 v2, v140, 27, 1
	v_lshlrev_b32_e32 v0, 4, v140
	v_lshrrev_b32_e32 v2, 22, v2
	v_add_u32_e32 v2, v0, v2
	v_and_b32_e32 v2, 0xfffffc00, v2
	v_sub_u32_e32 v2, v0, v2
	v_ashrrev_i32_e32 v1, 31, v140
	v_lshrrev_b32_e32 v3, 4, v2
	v_lshrrev_b32_e32 v1, 26, v1
	v_bitop3_b32 v3, v3, v2, 32 bitop3:0x6c
	v_ashrrev_i32_e32 v2, 31, v2
	v_add_u32_e32 v1, v140, v1
	v_lshrrev_b32_e32 v2, 26, v2
	v_ashrrev_i32_e32 v1, 6, v1
	v_add_u32_e32 v2, v3, v2
	v_lshlrev_b32_e32 v4, 3, v1
	v_ashrrev_i32_e32 v2, 6, v2
	v_lshlrev_b32_e32 v1, 5, v1
	v_and_b32_e32 v15, 32, v1
	v_mul_i32_i24_e32 v1, 64, v2
	v_sub_u32_e32 v1, v3, v1
	v_add_u32_e32 v3, 0x2000, v0
	v_ashrrev_i32_e32 v5, 31, v3
	v_lshrrev_b32_e32 v5, 22, v5
	v_add_u32_e32 v5, v3, v5
	v_ashrrev_i32_e32 v13, 10, v5
	v_mul_i32_i24_e32 v5, 0x400, v13
	v_sub_u32_e32 v3, v3, v5
	v_lshrrev_b32_e32 v5, 4, v3
	v_bitop3_b32 v3, v5, v3, 32 bitop3:0x6c
	v_ashrrev_i32_e32 v6, 31, v3
	v_lshrrev_b32_e32 v6, 26, v6
	v_and_b32_e32 v4, -16, v4
	v_ashrrev_i16_sdwa v17, v215, sext(v1) dst_sel:DWORD dst_unused:UNUSED_PAD src0_sel:DWORD src1_sel:BYTE_0
	v_lshlrev_b32_e32 v5, 3, v13
	v_add_u32_e32 v6, v3, v6
	v_add_u32_e32 v4, v2, v4
	v_add_u32_sdwa v1, v15, sext(v17) dst_sel:DWORD dst_unused:UNUSED_PAD src0_sel:DWORD src1_sel:WORD_0
	v_and_b32_e32 v5, -16, v5
	v_ashrrev_i32_e32 v14, 6, v6
	v_and_b32_e32 v6, 0xc0, v6
	v_add_u32_e32 v5, v14, v5
	v_sub_u32_e32 v3, v3, v6
	v_lshl_add_u32 v8, v4, 10, v1
	v_and_b32_e32 v19, 0xffffffe0, v4
	v_lshlrev_b32_e32 v6, 1, v4
	v_lshrrev_b32_e32 v4, 2, v4
	v_and_b32_e32 v22, 4, v4
	v_and_b32_e32 v24, 3, v2
	v_lshlrev_b32_e32 v4, 1, v5
	v_lshlrev_b32_e32 v7, 5, v13
	v_and_b32_e32 v21, 24, v6
	v_or_b32_e32 v2, v19, v24
	v_and_b32_e32 v20, 0xffffffe0, v5
	v_and_b32_e32 v23, 24, v4
	v_lshrrev_b32_e32 v4, 2, v5
	v_and_b32_e32 v26, 3, v14
	v_and_b32_e32 v16, 32, v7
	v_ashrrev_i16_sdwa v18, v215, sext(v3) dst_sel:DWORD dst_unused:UNUSED_PAD src0_sel:DWORD src1_sel:BYTE_0
	v_or3_b32 v2, v2, v21, v22
	v_and_b32_e32 v25, 4, v4
	v_or_b32_e32 v4, v20, v26
	v_add_u32_e32 v149, 0, v0
	v_add_u32_sdwa v3, v16, sext(v18) dst_sel:DWORD dst_unused:UNUSED_PAD src0_sel:DWORD src1_sel:WORD_0
	v_or3_b32 v4, v4, v23, v25
	v_lshl_add_u32 v64, v2, 9, v1
	v_add_u32_e32 v150, 0x10000, v149
	v_lshl_add_u32 v130, v5, 10, v3
	v_lshl_add_u32 v2, v4, 9, v3
	v_lshlrev_b64 v[6:7], 1, v[64:65]
	v_readfirstlane_b32 s7, v150
	v_mov_b32_e32 v3, v65
	v_add_u32_e32 v152, 0x12000, v149
	v_lshl_add_u64 v[0:1], s[28:29], 0, v[6:7]
	s_mov_b32 m0, s7
	v_lshlrev_b64 v[28:29], 1, v[2:3]
	v_readfirstlane_b32 s7, v152
	v_mov_b32_e32 v64, v8
	global_load_lds_dwordx4 v[0:1], off
	v_lshl_add_u64 v[2:3], s[28:29], 0, v[28:29]
	s_mov_b32 m0, s7
	v_lshlrev_b64 v[30:31], 1, v[64:65]
	v_readfirstlane_b32 s7, v149
	v_add_u32_e32 v153, 0x2000, v149
	global_load_lds_dwordx4 v[2:3], off
	v_lshl_add_u64 v[4:5], s[44:45], 0, v[30:31]
	s_mov_b32 m0, s7
	v_lshlrev_b64 v[32:33], 1, v[130:131]
	v_readfirstlane_b32 s7, v153
	v_add_u32_e32 v154, 0x14000, v149
	global_load_lds_dwordx4 v[4:5], off
	v_lshl_add_u64 v[8:9], s[44:45], 0, v[32:33]
	s_mov_b32 m0, s7
	v_readfirstlane_b32 s7, v154
	v_add_u32_e32 v155, 0x16000, v149
	global_load_lds_dwordx4 v[8:9], off
	v_lshl_add_u64 v[10:11], s[22:23], 0, v[6:7]
	s_mov_b32 m0, s7
	v_lshl_add_u64 v[6:7], s[22:23], 0, v[28:29]
	v_readfirstlane_b32 s7, v155
	s_add_u32 s22, s44, 0x40000
	v_add_u32_e32 v157, 0x4000, v149
	global_load_lds_dwordx4 v[10:11], off
	s_mov_b32 m0, s7
	s_addc_u32 s23, s45, 0
	v_readfirstlane_b32 s7, v157
	v_add_u32_e32 v158, 0x6000, v149
	global_load_lds_dwordx4 v[6:7], off
	v_lshl_add_u64 v[28:29], s[22:23], 0, v[30:31]
	s_mov_b32 m0, s7
	v_readfirstlane_b32 s7, v158
	global_load_lds_dwordx4 v[28:29], off
	v_lshl_add_u64 v[28:29], s[22:23], 0, v[32:33]
	s_mov_b32 m0, s7
	v_ashrrev_i32_e32 v12, 8, v140
	global_load_lds_dwordx4 v[28:29], off
	v_cmp_eq_u32_e32 vcc, 1, v12
	s_and_saveexec_b64 s[22:23], vcc
	s_cbranch_execz .LBB0_978
	s_barrier

; DI unsigned pk_f16(float lo, float hi) { f32x2_t v = {lo, hi}; return __builtin_bit_cast(unsigned, __builtin_convertvector(v, f16x2_t)); }
; DI float bflo(unsigned u) { return __uint_as_float(u << 16); }
; DI float bfhi(unsigned u) { return __uint_as_float(u & 0xffff0000u); }
; #define EPI_M _Pragma("unroll") for (int m = 0; m < 8; ++m)
; #define EPI_N _Pragma("unroll") for (int n = 0; n < 4; ++n)
; DI void p5_phase(const Params& p, char* lds) {
;     ...
;     EPI_IDX_N
;     {
;       u32x2 gq[2][4];
;       EPI_N gq[0][n] = tg[(0 * 4 + n) * 512 + tid];
;       EPI_M {
;         if (m < 7) EPI_N gq[(m + 1) & 1][n] = tg[((m + 1) * 4 + n) * 512 + tid];
;         EPI_N {
;           const u32x2 g = gq[m & 1][n];
;           u32x2 o; o[0] = pk_f16(ACC(m, n)[0] * bflo(g[0]), ACC(m, n)[1] * bfhi(g[0])); o[1] = pk_f16(ACC(m, n)[2] * bflo(g[1]), ACC(m, n)[3] * bfhi(g[1]));
;           tr[(m * 4 + n) * 512 + tid] = o;
;         }
;         __builtin_amdgcn_sched_barrier(0);
;       }
.LBB0_982:
	s_or_b64 exec, exec, s[8:9]
	s_waitcnt vmcnt(0)
	s_barrier
	s_getreg_b32 s2, hwreg(HW_REG_HW_ID, 0, 6)
	s_lshl_b32 s2, s2, 2
	s_and_b32 s2, s2, 0xfc
	s_add_i32 s2, s2, 0x20040
	v_mov_b32_e32 v64, s2
	ds_read_b32 v64, v64
	s_waitcnt lgkmcnt(0)
	v_readfirstlane_b32 s2, v64
	s_nop 1
	v_lshl_or_b32 v130, s2, 6, v214
	s_nop 0
	v_ashrrev_i32_e32 v131, 31, v130
	v_lshlrev_b64 v[162:163], 3, v[130:131]
	v_lshl_add_u64 v[132:133], s[10:11], 0, v[162:163]
	global_load_dwordx2 v[142:143], v[132:133], off
	v_add_u32_e32 v132, 0x200, v130
	v_ashrrev_i32_e32 v133, 31, v132
	v_lshlrev_b64 v[156:157], 3, v[132:133]
	v_lshl_add_u64 v[132:133], s[10:11], 0, v[156:157]
	global_load_dwordx2 v[164:165], v[132:133], off
	v_add_u32_e32 v132, 0x400, v130
	v_ashrrev_i32_e32 v133, 31, v132
	v_lshlrev_b64 v[152:153], 3, v[132:133]
	v_lshl_add_u64 v[132:133], s[10:11], 0, v[152:153]
	global_load_dwordx2 v[158:159], v[132:133], off
	v_add_u32_e32 v132, 0x600, v130
	v_ashrrev_i32_e32 v133, 31, v132
	v_lshlrev_b64 v[154:155], 3, v[132:133]
	v_lshl_add_u64 v[132:133], s[10:11], 0, v[154:155]
	global_load_dwordx2 v[160:161], v[132:133], off
	v_add_u32_e32 v132, 0x800, v130
	v_ashrrev_i32_e32 v133, 31, v132
	v_lshlrev_b64 v[132:133], 3, v[132:133]
	v_lshl_add_u64 v[134:135], s[10:11], 0, v[132:133]
	global_load_dwordx2 v[138:139], v[134:135], off
	v_add_u32_e32 v134, 0xa00, v130
	v_ashrrev_i32_e32 v135, 31, v134
	v_lshlrev_b64 v[134:135], 3, v[134:135]
	v_lshl_add_u64 v[136:137], s[10:11], 0, v[134:135]
	global_load_dwordx2 v[140:141], v[136:137], off
	v_add_u32_e32 v136, 0xc00, v130
	v_ashrrev_i32_e32 v137, 31, v136
	v_lshlrev_b64 v[136:137], 3, v[136:137]
	v_lshl_add_u64 v[144:145], s[10:11], 0, v[136:137]
	global_load_dwordx2 v[146:147], v[144:145], off
	v_add_u32_e32 v144, 0xe00, v130
	v_ashrrev_i32_e32 v145, 31, v144
	v_lshlrev_b64 v[148:149], 3, v[144:145]
	v_lshl_add_u64 v[144:145], s[10:11], 0, v[148:149]
	global_load_dwordx2 v[150:151], v[144:145], off
	s_waitcnt vmcnt(7)
	v_lshlrev_b32_e32 v144, 16, v142
	v_and_b32_e32 v145, 0xffff0000, v142
	v_lshlrev_b32_e32 v142, 16, v143
	v_and_b32_e32 v143, 0xffff0000, v143
	v_pk_mul_f32 v[126:127], v[126:127], v[144:145]
	v_pk_mul_f32 v[128:129], v[128:129], v[142:143]
	v_cvt_pk_f16_f32 v126, v126, v127
	v_cvt_pk_f16_f32 v127, v128, v129
	v_lshl_add_u64 v[128:129], s[12:13], 0, v[162:163]
	global_store_dwordx2 v[128:129], v[126:127], off sc0 sc1
	s_waitcnt vmcnt(7)
	v_lshlrev_b32_e32 v126, 16, v164
	v_and_b32_e32 v127, 0xffff0000, v164
	v_pk_mul_f32 v[122:123], v[122:123], v[126:127]
	v_lshlrev_b32_e32 v126, 16, v165
	v_and_b32_e32 v127, 0xffff0000, v165
	v_pk_mul_f32 v[124:125], v[124:125], v[126:127]
	v_cvt_pk_f16_f32 v122, v122, v123
	v_cvt_pk_f16_f32 v123, v124, v125
	v_lshl_add_u64 v[124:125], s[12:13], 0, v[156:157]
	global_store_dwordx2 v[124:125], v[122:123], off sc0 sc1
	s_waitcnt vmcnt(7)
	v_lshlrev_b32_e32 v122, 16, v158
	v_and_b32_e32 v123, 0xffff0000, v158
	v_pk_mul_f32 v[118:119], v[118:119], v[122:123]
	v_lshlrev_b32_e32 v122, 16, v159
	v_and_b32_e32 v123, 0xffff0000, v159
	v_pk_mul_f32 v[120:121], v[120:121], v[122:123]
	v_cvt_pk_f16_f32 v118, v118, v119
	v_cvt_pk_f16_f32 v119, v120, v121
	v_lshl_add_u64 v[120:121], s[12:13], 0, v[152:153]
	global_store_dwordx2 v[120:121], v[118:119], off sc0 sc1
	s_waitcnt vmcnt(7)
	v_lshlrev_b32_e32 v118, 16, v160
	v_and_b32_e32 v119, 0xffff0000, v160
	v_pk_mul_f32 v[114:115], v[114:115], v[118:119]
	v_lshlrev_b32_e32 v118, 16, v161
	v_and_b32_e32 v119, 0xffff0000, v161
	v_pk_mul_f32 v[116:117], v[116:117], v[118:119]
	v_cvt_pk_f16_f32 v114, v114, v115
	v_cvt_pk_f16_f32 v115, v116, v117
	v_lshl_add_u64 v[116:117], s[12:13], 0, v[154:155]
	global_store_dwordx2 v[116:117], v[114:115], off sc0 sc1
	v_add_u32_e32 v114, 0x1000, v130
	v_add_u32_e32 v118, 0x1200, v130
	v_add_u32_e32 v122, 0x1400, v130
	v_add_u32_e32 v126, 0x1600, v130
	v_ashrrev_i32_e32 v115, 31, v114
	v_ashrrev_i32_e32 v119, 31, v118
	v_ashrrev_i32_e32 v123, 31, v122
	v_ashrrev_i32_e32 v127, 31, v126
	v_lshlrev_b64 v[114:115], 3, v[114:115]
	v_lshlrev_b64 v[118:119], 3, v[118:119]
	v_lshlrev_b64 v[122:123], 3, v[122:123]
	v_lshlrev_b64 v[126:127], 3, v[126:127]
	v_lshl_add_u64 v[116:117], s[10:11], 0, v[114:115]
	v_lshl_add_u64 v[120:121], s[10:11], 0, v[118:119]
	v_lshl_add_u64 v[124:125], s[10:11], 0, v[122:123]
	v_lshl_add_u64 v[128:129], s[10:11], 0, v[126:127]
	global_load_dwordx2 v[116:117], v[116:117], off
	s_nop 0
	global_load_dwordx2 v[120:121], v[120:121], off
	s_nop 0
	global_load_dwordx2 v[124:125], v[124:125], off
	s_nop 0
	global_load_dwordx2 v[128:129], v[128:129], off
	s_waitcnt vmcnt(11)
	v_lshlrev_b32_e32 v142, 16, v138
	v_and_b32_e32 v143, 0xffff0000, v138
	v_lshlrev_b32_e32 v138, 16, v139
	v_and_b32_e32 v139, 0xffff0000, v139
	v_pk_mul_f32 v[110:111], v[110:111], v[142:143]
	v_pk_mul_f32 v[112:113], v[112:113], v[138:139]
	v_cvt_pk_f16_f32 v110, v110, v111
	v_cvt_pk_f16_f32 v111, v112, v113
	v_lshl_add_u64 v[112:113], s[12:13], 0, v[132:133]
	global_store_dwordx2 v[112:113], v[110:111], off sc0 sc1
	s_waitcnt vmcnt(11)
	v_lshlrev_b32_e32 v110, 16, v140
	v_and_b32_e32 v111, 0xffff0000, v140
	v_pk_mul_f32 v[102:103], v[102:103], v[110:111]
	v_lshlrev_b32_e32 v110, 16, v141
	v_and_b32_e32 v111, 0xffff0000, v141
	v_pk_mul_f32 v[104:105], v[104:105], v[110:111]
	v_cvt_pk_f16_f32 v102, v102, v103
	v_cvt_pk_f16_f32 v103, v104, v105
	v_lshl_add_u64 v[104:105], s[12:13], 0, v[134:135]
	global_store_dwordx2 v[104:105], v[102:103], off sc0 sc1
	s_waitcnt vmcnt(11)
; DI unsigned pk_f16(float lo, float hi) { f32x2_t v = {lo, hi}; return __builtin_bit_cast(unsigned, __builtin_convertvector(v, f16x2_t)); }
; DI float bflo(unsigned u) { return __uint_as_float(u << 16); }
; DI float bfhi(unsigned u) { return __uint_as_float(u & 0xffff0000u); }
; #define EPI_M _Pragma("unroll") for (int m = 0; m < 8; ++m)
; #define EPI_N _Pragma("unroll") for (int n = 0; n < 4; ++n)
; DI void p5_phase(const Params& p, char* lds) {
;     ...
;     EPI_IDX_N
;     {
;       u32x2 gq[2][4];
;       EPI_N gq[0][n] = tg[(0 * 4 + n) * 512 + tid];
;       EPI_M {
;         if (m < 7) EPI_N gq[(m + 1) & 1][n] = tg[((m + 1) * 4 + n) * 512 + tid];
;         EPI_N {
;           const u32x2 g = gq[m & 1][n];
;           u32x2 o; o[0] = pk_f16(ACC(m, n)[0] * bflo(g[0]), ACC(m, n)[1] * bfhi(g[0])); o[1] = pk_f16(ACC(m, n)[2] * bflo(g[1]), ACC(m, n)[3] * bfhi(g[1]));
;           tr[(m * 4 + n) * 512 + tid] = o;
;         }
;         __builtin_amdgcn_sched_barrier(0);
;       }
	v_lshlrev_b32_e32 v102, 16, v146
	v_and_b32_e32 v103, 0xffff0000, v146
	v_lshlrev_b32_e32 v104, 16, v147
	v_and_b32_e32 v105, 0xffff0000, v147
	v_pk_mul_f32 v[102:103], v[106:107], v[102:103]
	v_pk_mul_f32 v[104:105], v[108:109], v[104:105]
	v_cvt_pk_f16_f32 v102, v102, v103
	v_cvt_pk_f16_f32 v103, v104, v105
	v_lshl_add_u64 v[104:105], s[12:13], 0, v[136:137]
	global_store_dwordx2 v[104:105], v[102:103], off sc0 sc1
	s_waitcnt vmcnt(11)
	v_lshlrev_b32_e32 v102, 16, v150
	v_and_b32_e32 v103, 0xffff0000, v150
	v_pk_mul_f32 v[98:99], v[98:99], v[102:103]
	v_lshlrev_b32_e32 v102, 16, v151
	v_and_b32_e32 v103, 0xffff0000, v151
	v_pk_mul_f32 v[100:101], v[100:101], v[102:103]
	v_cvt_pk_f16_f32 v98, v98, v99
	v_cvt_pk_f16_f32 v99, v100, v101
	v_lshl_add_u64 v[100:101], s[12:13], 0, v[148:149]
	global_store_dwordx2 v[100:101], v[98:99], off sc0 sc1
	v_add_u32_e32 v98, 0x1800, v130
	v_add_u32_e32 v102, 0x1a00, v130
	v_add_u32_e32 v106, 0x1c00, v130
	v_add_u32_e32 v110, 0x1e00, v130
	v_ashrrev_i32_e32 v99, 31, v98
	v_ashrrev_i32_e32 v103, 31, v102
	v_ashrrev_i32_e32 v107, 31, v106
	v_ashrrev_i32_e32 v111, 31, v110
	v_lshlrev_b64 v[98:99], 3, v[98:99]
	v_lshlrev_b64 v[102:103], 3, v[102:103]
	v_lshlrev_b64 v[106:107], 3, v[106:107]
	v_lshlrev_b64 v[110:111], 3, v[110:111]
	v_lshl_add_u64 v[100:101], s[10:11], 0, v[98:99]
	v_lshl_add_u64 v[104:105], s[10:11], 0, v[102:103]
	v_lshl_add_u64 v[108:109], s[10:11], 0, v[106:107]
	v_lshl_add_u64 v[112:113], s[10:11], 0, v[110:111]
	global_load_dwordx2 v[100:101], v[100:101], off
	s_nop 0
	global_load_dwordx2 v[104:105], v[104:105], off
	s_nop 0
	global_load_dwordx2 v[108:109], v[108:109], off
	s_nop 0
	global_load_dwordx2 v[112:113], v[112:113], off
	s_waitcnt vmcnt(11)
	v_lshlrev_b32_e32 v132, 16, v116
	v_and_b32_e32 v133, 0xffff0000, v116
	v_lshlrev_b32_e32 v116, 16, v117
	v_and_b32_e32 v117, 0xffff0000, v117
	v_pk_mul_f32 v[94:95], v[94:95], v[132:133]
	v_pk_mul_f32 v[96:97], v[96:97], v[116:117]
	v_cvt_pk_f16_f32 v94, v94, v95
	v_cvt_pk_f16_f32 v95, v96, v97
	v_lshl_add_u64 v[96:97], s[12:13], 0, v[114:115]
	global_store_dwordx2 v[96:97], v[94:95], off sc0 sc1
	s_waitcnt vmcnt(11)
	v_lshlrev_b32_e32 v94, 16, v120
	v_and_b32_e32 v95, 0xffff0000, v120
	v_pk_mul_f32 v[86:87], v[86:87], v[94:95]
	v_lshlrev_b32_e32 v94, 16, v121
	v_and_b32_e32 v95, 0xffff0000, v121
	v_pk_mul_f32 v[88:89], v[88:89], v[94:95]
	v_cvt_pk_f16_f32 v86, v86, v87
	v_cvt_pk_f16_f32 v87, v88, v89
	v_lshl_add_u64 v[88:89], s[12:13], 0, v[118:119]
	global_store_dwordx2 v[88:89], v[86:87], off sc0 sc1
	s_waitcnt vmcnt(11)
	v_lshlrev_b32_e32 v86, 16, v124
	v_and_b32_e32 v87, 0xffff0000, v124
	v_lshlrev_b32_e32 v88, 16, v125
	v_and_b32_e32 v89, 0xffff0000, v125
	v_pk_mul_f32 v[86:87], v[90:91], v[86:87]
	v_pk_mul_f32 v[88:89], v[92:93], v[88:89]
	v_cvt_pk_f16_f32 v86, v86, v87
	v_cvt_pk_f16_f32 v87, v88, v89
	v_lshl_add_u64 v[88:89], s[12:13], 0, v[122:123]
	global_store_dwordx2 v[88:89], v[86:87], off sc0 sc1
	s_waitcnt vmcnt(11)
	v_lshlrev_b32_e32 v86, 16, v128
	v_and_b32_e32 v87, 0xffff0000, v128
	v_pk_mul_f32 v[82:83], v[82:83], v[86:87]
	v_lshlrev_b32_e32 v86, 16, v129
	v_and_b32_e32 v87, 0xffff0000, v129
	v_pk_mul_f32 v[84:85], v[84:85], v[86:87]
	v_cvt_pk_f16_f32 v82, v82, v83
	v_cvt_pk_f16_f32 v83, v84, v85
	v_lshl_add_u64 v[84:85], s[12:13], 0, v[126:127]
	global_store_dwordx2 v[84:85], v[82:83], off sc0 sc1
	v_add_u32_e32 v82, 0x2000, v130
	v_add_u32_e32 v86, 0x2200, v130
	v_add_u32_e32 v90, 0x2400, v130
	v_add_u32_e32 v94, 0x2600, v130
	v_ashrrev_i32_e32 v83, 31, v82
	v_ashrrev_i32_e32 v87, 31, v86
	v_ashrrev_i32_e32 v91, 31, v90
	v_ashrrev_i32_e32 v95, 31, v94
	v_lshlrev_b64 v[82:83], 3, v[82:83]
	v_lshlrev_b64 v[86:87], 3, v[86:87]
	v_lshlrev_b64 v[90:91], 3, v[90:91]
	v_lshlrev_b64 v[94:95], 3, v[94:95]
	v_lshl_add_u64 v[84:85], s[10:11], 0, v[82:83]
	v_lshl_add_u64 v[88:89], s[10:11], 0, v[86:87]
	v_lshl_add_u64 v[92:93], s[10:11], 0, v[90:91]
	v_lshl_add_u64 v[96:97], s[10:11], 0, v[94:95]
	global_load_dwordx2 v[84:85], v[84:85], off
	s_nop 0
	global_load_dwordx2 v[88:89], v[88:89], off
	s_nop 0
	global_load_dwordx2 v[92:93], v[92:93], off
	s_nop 0
	global_load_dwordx2 v[96:97], v[96:97], off
	s_waitcnt vmcnt(11)
	v_lshlrev_b32_e32 v114, 16, v100
	v_and_b32_e32 v115, 0xffff0000, v100
	v_lshlrev_b32_e32 v100, 16, v101
	v_and_b32_e32 v101, 0xffff0000, v101
	v_pk_mul_f32 v[78:79], v[78:79], v[114:115]
	v_pk_mul_f32 v[80:81], v[80:81], v[100:101]
	v_cvt_pk_f16_f32 v78, v78, v79
	v_cvt_pk_f16_f32 v79, v80, v81
	v_lshl_add_u64 v[80:81], s[12:13], 0, v[98:99]
	global_store_dwordx2 v[80:81], v[78:79], off sc0 sc1
	s_waitcnt vmcnt(11)
	v_lshlrev_b32_e32 v78, 16, v104
	v_and_b32_e32 v79, 0xffff0000, v104
	v_pk_mul_f32 v[70:71], v[70:71], v[78:79]
	v_lshlrev_b32_e32 v78, 16, v105
	v_and_b32_e32 v79, 0xffff0000, v105
	v_pk_mul_f32 v[72:73], v[72:73], v[78:79]
	v_cvt_pk_f16_f32 v70, v70, v71
	v_cvt_pk_f16_f32 v71, v72, v73
	v_lshl_add_u64 v[72:73], s[12:13], 0, v[102:103]
	global_store_dwordx2 v[72:73], v[70:71], off sc0 sc1
	s_waitcnt vmcnt(11)
	v_lshlrev_b32_e32 v70, 16, v108
	v_and_b32_e32 v71, 0xffff0000, v108
	v_lshlrev_b32_e32 v72, 16, v109
	v_and_b32_e32 v73, 0xffff0000, v109
	v_pk_mul_f32 v[70:71], v[74:75], v[70:71]
	v_pk_mul_f32 v[72:73], v[76:77], v[72:73]
	v_cvt_pk_f16_f32 v70, v70, v71
	v_cvt_pk_f16_f32 v71, v72, v73
	v_lshl_add_u64 v[72:73], s[12:13], 0, v[106:107]
	global_store_dwordx2 v[72:73], v[70:71], off sc0 sc1
	s_waitcnt vmcnt(11)
; DI unsigned pk_f16(float lo, float hi) { f32x2_t v = {lo, hi}; return __builtin_bit_cast(unsigned, __builtin_convertvector(v, f16x2_t)); }
; DI float bflo(unsigned u) { return __uint_as_float(u << 16); }
; DI float bfhi(unsigned u) { return __uint_as_float(u & 0xffff0000u); }
; #define EPI_M _Pragma("unroll") for (int m = 0; m < 8; ++m)
; #define EPI_N _Pragma("unroll") for (int n = 0; n < 4; ++n)
; DI void p5_phase(const Params& p, char* lds) {
;     ...
;     EPI_IDX_N
;     {
;       u32x2 gq[2][4];
;       EPI_N gq[0][n] = tg[(0 * 4 + n) * 512 + tid];
;       EPI_M {
;         if (m < 7) EPI_N gq[(m + 1) & 1][n] = tg[((m + 1) * 4 + n) * 512 + tid];
;         EPI_N {
;           const u32x2 g = gq[m & 1][n];
;           u32x2 o; o[0] = pk_f16(ACC(m, n)[0] * bflo(g[0]), ACC(m, n)[1] * bfhi(g[0])); o[1] = pk_f16(ACC(m, n)[2] * bflo(g[1]), ACC(m, n)[3] * bfhi(g[1]));
;           tr[(m * 4 + n) * 512 + tid] = o;
;         }
;         __builtin_amdgcn_sched_barrier(0);
;       }
	v_lshlrev_b32_e32 v70, 16, v112
	v_and_b32_e32 v71, 0xffff0000, v112
	v_pk_mul_f32 v[66:67], v[66:67], v[70:71]
	v_lshlrev_b32_e32 v70, 16, v113
	v_and_b32_e32 v71, 0xffff0000, v113
	v_pk_mul_f32 v[68:69], v[68:69], v[70:71]
	v_cvt_pk_f16_f32 v66, v66, v67
	v_cvt_pk_f16_f32 v67, v68, v69
	v_lshl_add_u64 v[68:69], s[12:13], 0, v[110:111]
	global_store_dwordx2 v[68:69], v[66:67], off sc0 sc1
	v_add_u32_e32 v66, 0x2800, v130
	v_add_u32_e32 v70, 0x2a00, v130
	v_add_u32_e32 v74, 0x2c00, v130
	v_add_u32_e32 v78, 0x2e00, v130
	v_ashrrev_i32_e32 v67, 31, v66
	v_ashrrev_i32_e32 v71, 31, v70
	v_ashrrev_i32_e32 v75, 31, v74
	v_ashrrev_i32_e32 v79, 31, v78
	v_lshlrev_b64 v[66:67], 3, v[66:67]
	v_lshlrev_b64 v[70:71], 3, v[70:71]
	v_lshlrev_b64 v[74:75], 3, v[74:75]
	v_lshlrev_b64 v[78:79], 3, v[78:79]
	v_lshl_add_u64 v[68:69], s[10:11], 0, v[66:67]
	v_lshl_add_u64 v[72:73], s[10:11], 0, v[70:71]
	v_lshl_add_u64 v[76:77], s[10:11], 0, v[74:75]
	v_lshl_add_u64 v[80:81], s[10:11], 0, v[78:79]
	global_load_dwordx2 v[68:69], v[68:69], off
	s_nop 0
	global_load_dwordx2 v[72:73], v[72:73], off
	s_nop 0
	global_load_dwordx2 v[76:77], v[76:77], off
	s_nop 0
	global_load_dwordx2 v[80:81], v[80:81], off
	s_waitcnt vmcnt(11)
	v_lshlrev_b32_e32 v98, 16, v84
	v_and_b32_e32 v99, 0xffff0000, v84
	v_lshlrev_b32_e32 v84, 16, v85
	v_and_b32_e32 v85, 0xffff0000, v85
	v_pk_mul_f32 v[60:61], v[60:61], v[98:99]
	v_pk_mul_f32 v[62:63], v[62:63], v[84:85]
	v_cvt_pk_f16_f32 v60, v60, v61
	v_cvt_pk_f16_f32 v61, v62, v63
	v_lshl_add_u64 v[62:63], s[12:13], 0, v[82:83]
	global_store_dwordx2 v[62:63], v[60:61], off sc0 sc1
	s_waitcnt vmcnt(11)
	v_lshlrev_b32_e32 v60, 16, v88
	v_and_b32_e32 v61, 0xffff0000, v88
	v_pk_mul_f32 v[56:57], v[56:57], v[60:61]
	v_lshlrev_b32_e32 v60, 16, v89
	v_and_b32_e32 v61, 0xffff0000, v89
	v_pk_mul_f32 v[58:59], v[58:59], v[60:61]
	v_cvt_pk_f16_f32 v56, v56, v57
	v_cvt_pk_f16_f32 v57, v58, v59
	v_lshl_add_u64 v[58:59], s[12:13], 0, v[86:87]
	global_store_dwordx2 v[58:59], v[56:57], off sc0 sc1
	s_waitcnt vmcnt(11)
	v_lshlrev_b32_e32 v56, 16, v92
	v_and_b32_e32 v57, 0xffff0000, v92
	v_pk_mul_f32 v[52:53], v[52:53], v[56:57]
	v_lshlrev_b32_e32 v56, 16, v93
	v_and_b32_e32 v57, 0xffff0000, v93
	v_pk_mul_f32 v[54:55], v[54:55], v[56:57]
	v_cvt_pk_f16_f32 v52, v52, v53
	v_cvt_pk_f16_f32 v53, v54, v55
	v_lshl_add_u64 v[54:55], s[12:13], 0, v[90:91]
	global_store_dwordx2 v[54:55], v[52:53], off sc0 sc1
	s_waitcnt vmcnt(11)
	v_lshlrev_b32_e32 v52, 16, v96
	v_and_b32_e32 v53, 0xffff0000, v96
	v_pk_mul_f32 v[48:49], v[48:49], v[52:53]
	v_lshlrev_b32_e32 v52, 16, v97
	v_and_b32_e32 v53, 0xffff0000, v97
	v_pk_mul_f32 v[50:51], v[50:51], v[52:53]
	v_cvt_pk_f16_f32 v48, v48, v49
	v_cvt_pk_f16_f32 v49, v50, v51
	v_lshl_add_u64 v[50:51], s[12:13], 0, v[94:95]
	global_store_dwordx2 v[50:51], v[48:49], off sc0 sc1
	v_add_u32_e32 v48, 0x3000, v130
	v_add_u32_e32 v52, 0x3200, v130
	v_add_u32_e32 v56, 0x3400, v130
	v_add_u32_e32 v60, 0x3600, v130
	v_ashrrev_i32_e32 v49, 31, v48
	v_ashrrev_i32_e32 v53, 31, v52
	v_ashrrev_i32_e32 v57, 31, v56
	v_ashrrev_i32_e32 v61, 31, v60
	v_lshlrev_b64 v[48:49], 3, v[48:49]
	v_lshlrev_b64 v[52:53], 3, v[52:53]
	v_lshlrev_b64 v[56:57], 3, v[56:57]
	v_lshlrev_b64 v[60:61], 3, v[60:61]
	v_lshl_add_u64 v[50:51], s[10:11], 0, v[48:49]
	v_lshl_add_u64 v[54:55], s[10:11], 0, v[52:53]
	v_lshl_add_u64 v[58:59], s[10:11], 0, v[56:57]
	v_lshl_add_u64 v[62:63], s[10:11], 0, v[60:61]
	global_load_dwordx2 v[50:51], v[50:51], off
	s_nop 0
	global_load_dwordx2 v[54:55], v[54:55], off
	s_nop 0
	global_load_dwordx2 v[58:59], v[58:59], off
	s_nop 0
	global_load_dwordx2 v[62:63], v[62:63], off
	s_waitcnt vmcnt(11)
	v_lshlrev_b32_e32 v82, 16, v68
	v_and_b32_e32 v83, 0xffff0000, v68
	v_lshlrev_b32_e32 v68, 16, v69
	v_and_b32_e32 v69, 0xffff0000, v69
	v_pk_mul_f32 v[44:45], v[44:45], v[82:83]
	v_pk_mul_f32 v[46:47], v[46:47], v[68:69]
	v_cvt_pk_f16_f32 v44, v44, v45
	v_cvt_pk_f16_f32 v45, v46, v47
	v_lshl_add_u64 v[46:47], s[12:13], 0, v[66:67]
	global_store_dwordx2 v[46:47], v[44:45], off sc0 sc1
	s_waitcnt vmcnt(11)
	v_lshlrev_b32_e32 v44, 16, v72
	v_and_b32_e32 v45, 0xffff0000, v72
	v_pk_mul_f32 v[40:41], v[40:41], v[44:45]
	v_lshlrev_b32_e32 v44, 16, v73
	v_and_b32_e32 v45, 0xffff0000, v73
	v_pk_mul_f32 v[42:43], v[42:43], v[44:45]
	v_cvt_pk_f16_f32 v40, v40, v41
	v_cvt_pk_f16_f32 v41, v42, v43
	v_lshl_add_u64 v[42:43], s[12:13], 0, v[70:71]
	global_store_dwordx2 v[42:43], v[40:41], off sc0 sc1
	s_waitcnt vmcnt(11)
	v_lshlrev_b32_e32 v40, 16, v76
	v_and_b32_e32 v41, 0xffff0000, v76
	v_pk_mul_f32 v[36:37], v[36:37], v[40:41]
	v_lshlrev_b32_e32 v40, 16, v77
	v_and_b32_e32 v41, 0xffff0000, v77
	v_pk_mul_f32 v[38:39], v[38:39], v[40:41]
	v_cvt_pk_f16_f32 v36, v36, v37
	v_cvt_pk_f16_f32 v37, v38, v39
	v_lshl_add_u64 v[38:39], s[12:13], 0, v[74:75]
	global_store_dwordx2 v[38:39], v[36:37], off sc0 sc1
	s_waitcnt vmcnt(11)
	v_lshlrev_b32_e32 v36, 16, v80
	v_and_b32_e32 v37, 0xffff0000, v80
	v_pk_mul_f32 v[32:33], v[32:33], v[36:37]
	v_lshlrev_b32_e32 v36, 16, v81
	v_and_b32_e32 v37, 0xffff0000, v81
	v_pk_mul_f32 v[34:35], v[34:35], v[36:37]
	v_cvt_pk_f16_f32 v32, v32, v33
	v_cvt_pk_f16_f32 v33, v34, v35
	v_lshl_add_u64 v[34:35], s[12:13], 0, v[78:79]
	global_store_dwordx2 v[34:35], v[32:33], off sc0 sc1
	v_add_u32_e32 v32, 0x3800, v130
	v_add_u32_e32 v36, 0x3a00, v130
	v_add_u32_e32 v40, 0x3c00, v130
	v_add_u32_e32 v44, 0x3e00, v130
	v_ashrrev_i32_e32 v33, 31, v32
	v_ashrrev_i32_e32 v37, 31, v36
	v_ashrrev_i32_e32 v41, 31, v40
	v_ashrrev_i32_e32 v45, 31, v44
	v_lshlrev_b64 v[32:33], 3, v[32:33]
	v_lshlrev_b64 v[36:37], 3, v[36:37]
	v_lshlrev_b64 v[40:41], 3, v[40:41]
	v_lshlrev_b64 v[44:45], 3, v[44:45]
	v_lshl_add_u64 v[34:35], s[10:11], 0, v[32:33]
	v_lshl_add_u64 v[38:39], s[10:11], 0, v[36:37]
	v_lshl_add_u64 v[42:43], s[10:11], 0, v[40:41]
	v_lshl_add_u64 v[46:47], s[10:11], 0, v[44:45]
	global_load_dwordx2 v[34:35], v[34:35], off
	s_nop 0
	global_load_dwordx2 v[38:39], v[38:39], off
	s_nop 0
	global_load_dwordx2 v[42:43], v[42:43], off
	s_nop 0
	global_load_dwordx2 v[46:47], v[46:47], off
	s_waitcnt vmcnt(11)
; DI unsigned pk_f16(float lo, float hi) { f32x2_t v = {lo, hi}; return __builtin_bit_cast(unsigned, __builtin_convertvector(v, f16x2_t)); }
; DI float bflo(unsigned u) { return __uint_as_float(u << 16); }
; DI float bfhi(unsigned u) { return __uint_as_float(u & 0xffff0000u); }
; #define EPI_M _Pragma("unroll") for (int m = 0; m < 8; ++m)
; #define EPI_N _Pragma("unroll") for (int n = 0; n < 4; ++n)
; DI void p5_phase(const Params& p, char* lds) {
;     ...
;     EPI_IDX_N
;     {
;       u32x2 gq[2][4];
;       EPI_N gq[0][n] = tg[(0 * 4 + n) * 512 + tid];
;       EPI_M {
;         if (m < 7) EPI_N gq[(m + 1) & 1][n] = tg[((m + 1) * 4 + n) * 512 + tid];
;         EPI_N {
;           const u32x2 g = gq[m & 1][n];
;           u32x2 o; o[0] = pk_f16(ACC(m, n)[0] * bflo(g[0]), ACC(m, n)[1] * bfhi(g[0])); o[1] = pk_f16(ACC(m, n)[2] * bflo(g[1]), ACC(m, n)[3] * bfhi(g[1]));
;           tr[(m * 4 + n) * 512 + tid] = o;
;         }
;         __builtin_amdgcn_sched_barrier(0);
;       }
;     }
;     zero_acc(acc);
;     gemm256(xb + (size_t)row0 * D, D, win + (size_t)(4608 + col0) * D, win + (size_t)(4608 + col0 + 128) * D, D, 16, acc, lds);
	v_lshlrev_b32_e32 v66, 16, v50
	v_and_b32_e32 v67, 0xffff0000, v50
	v_lshlrev_b32_e32 v50, 16, v51
	v_and_b32_e32 v51, 0xffff0000, v51
	v_pk_mul_f32 v[28:29], v[28:29], v[66:67]
	v_pk_mul_f32 v[30:31], v[30:31], v[50:51]
	v_cvt_pk_f16_f32 v28, v28, v29
	v_cvt_pk_f16_f32 v29, v30, v31
	v_lshl_add_u64 v[30:31], s[12:13], 0, v[48:49]
	global_store_dwordx2 v[30:31], v[28:29], off sc0 sc1
	s_waitcnt vmcnt(11)
	v_lshlrev_b32_e32 v28, 16, v54
	v_and_b32_e32 v29, 0xffff0000, v54
	v_pk_mul_f32 v[24:25], v[24:25], v[28:29]
	v_lshlrev_b32_e32 v28, 16, v55
	v_and_b32_e32 v29, 0xffff0000, v55
	v_pk_mul_f32 v[26:27], v[26:27], v[28:29]
	v_cvt_pk_f16_f32 v24, v24, v25
	v_cvt_pk_f16_f32 v25, v26, v27
	v_lshl_add_u64 v[26:27], s[12:13], 0, v[52:53]
	global_store_dwordx2 v[26:27], v[24:25], off sc0 sc1
	s_waitcnt vmcnt(11)
	v_lshlrev_b32_e32 v24, 16, v58
	v_and_b32_e32 v25, 0xffff0000, v58
	v_pk_mul_f32 v[20:21], v[20:21], v[24:25]
	v_lshlrev_b32_e32 v24, 16, v59
	v_and_b32_e32 v25, 0xffff0000, v59
	v_pk_mul_f32 v[22:23], v[22:23], v[24:25]
	v_cvt_pk_f16_f32 v20, v20, v21
	v_cvt_pk_f16_f32 v21, v22, v23
	v_lshl_add_u64 v[22:23], s[12:13], 0, v[56:57]
	global_store_dwordx2 v[22:23], v[20:21], off sc0 sc1
	s_waitcnt vmcnt(11)
	v_lshlrev_b32_e32 v20, 16, v62
	v_and_b32_e32 v21, 0xffff0000, v62
	v_pk_mul_f32 v[16:17], v[16:17], v[20:21]
	v_lshlrev_b32_e32 v20, 16, v63
	v_and_b32_e32 v21, 0xffff0000, v63
	v_pk_mul_f32 v[18:19], v[18:19], v[20:21]
	v_cvt_pk_f16_f32 v16, v16, v17
	v_cvt_pk_f16_f32 v17, v18, v19
	v_lshl_add_u64 v[18:19], s[12:13], 0, v[60:61]
	global_store_dwordx2 v[18:19], v[16:17], off sc0 sc1
	s_waitcnt vmcnt(7)
	v_lshlrev_b32_e32 v16, 16, v34
	v_and_b32_e32 v17, 0xffff0000, v34
	v_pk_mul_f32 v[12:13], v[12:13], v[16:17]
	v_lshlrev_b32_e32 v16, 16, v35
	v_and_b32_e32 v17, 0xffff0000, v35
	v_pk_mul_f32 v[14:15], v[14:15], v[16:17]
	v_cvt_pk_f16_f32 v12, v12, v13
	v_cvt_pk_f16_f32 v13, v14, v15
	v_lshl_add_u64 v[14:15], s[12:13], 0, v[32:33]
	global_store_dwordx2 v[14:15], v[12:13], off sc0 sc1
	s_waitcnt vmcnt(7)
	v_lshlrev_b32_e32 v12, 16, v38
	v_and_b32_e32 v13, 0xffff0000, v38
	v_pk_mul_f32 v[8:9], v[8:9], v[12:13]
	v_lshlrev_b32_e32 v12, 16, v39
	v_and_b32_e32 v13, 0xffff0000, v39
	v_pk_mul_f32 v[10:11], v[10:11], v[12:13]
	v_cvt_pk_f16_f32 v8, v8, v9
	v_cvt_pk_f16_f32 v9, v10, v11
	v_lshl_add_u64 v[10:11], s[12:13], 0, v[36:37]
	global_store_dwordx2 v[10:11], v[8:9], off sc0 sc1
	s_waitcnt vmcnt(7)
	v_lshlrev_b32_e32 v8, 16, v42
	v_and_b32_e32 v9, 0xffff0000, v42
	v_pk_mul_f32 v[4:5], v[4:5], v[8:9]
	v_lshlrev_b32_e32 v8, 16, v43
	v_and_b32_e32 v9, 0xffff0000, v43
	v_pk_mul_f32 v[6:7], v[6:7], v[8:9]
	v_cvt_pk_f16_f32 v4, v4, v5
	v_cvt_pk_f16_f32 v5, v6, v7
	v_lshl_add_u64 v[6:7], s[12:13], 0, v[40:41]
	global_store_dwordx2 v[6:7], v[4:5], off sc0 sc1
	s_waitcnt vmcnt(7)
	v_lshlrev_b32_e32 v4, 16, v46
	v_and_b32_e32 v5, 0xffff0000, v46
	v_pk_mul_f32 v[0:1], v[0:1], v[4:5]
	v_lshlrev_b32_e32 v4, 16, v47
	v_and_b32_e32 v5, 0xffff0000, v47
	v_pk_mul_f32 v[2:3], v[2:3], v[4:5]
	v_cvt_pk_f16_f32 v0, v0, v1
	v_cvt_pk_f16_f32 v1, v2, v3
	v_lshl_add_u64 v[2:3], s[12:13], 0, v[44:45]
	global_store_dwordx2 v[2:3], v[0:1], off sc0 sc1
	s_lshl_b64 s[2:3], s[38:39], 11
	s_add_u32 s2, s90, s2
	s_addc_u32 s3, s91, s3
	s_add_u32 s22, s2, 0x900000
	s_addc_u32 s23, s3, 0
	s_add_u32 s8, s2, 0x940000
	s_getreg_b32 s2, hwreg(HW_REG_HW_ID, 0, 6)
	s_addc_u32 s9, s3, 0
	s_lshl_b32 s2, s2, 2
	s_and_b32 s2, s2, 0xfc
	s_add_i32 s2, s2, 0x20040
	v_mov_b32_e32 v0, s2
	ds_read_b32 v0, v0
	v_mov_b32_e32 v131, v65
	s_waitcnt lgkmcnt(0)
; DI int my_tid() { int t = tid_raw(); asm volatile("" : "+v"(t)); return t; }
; #define STAGE_A(b, h, kt) { const u16* ap_ = A + (size_t)((h) * ahalf + (unsigned)(kt) * 64u); glds16(ap_ + ao0, l0 + SA_(b, h)); glds16(ap_ + ao1, l0 + SA_(b, h) + 8192); }
; #define STAGE_B(b, h, kt) { const u16* bp_ = ((h) ? B1 : B0) + (unsigned)(kt) * 64u; glds16(bp_ + bo0, l0 + SB_(b, h)); glds16(bp_ + bo1, l0 + SB_(b, h) + 8192); }
; #define WAIT_V(n) asm volatile("s_waitcnt vmcnt(" #n ")" ::: "memory");
; #define BAR __builtin_amdgcn_s_barrier();
; DI void gemm256(const u16* __restrict__ A, int lda, const u16* __restrict__ B0, const u16* __restrict__ B1, int ldb, int nt, acc_t& acc, char* lds) {
;   const int tid = my_tid();
;   const int lane = tid & 63, wid = tid >> 6, wr = wid >> 2, wc = wid & 3, fr = lane & 15, fq = lane >> 4;
;   int r0, c0, r1, c1;
;   stage_rc(tid * 16, r0, c0); stage_rc(tid * 16 + 8192, r1, c1);
;   const unsigned ao0 = (unsigned)(r0 * lda + c0), ao1 = (unsigned)(r1 * lda + c1);
;   const unsigned ahalf = 128u * (unsigned)lda;
;   const int p0 = (r0 & ~31) + (((r0 & 15) >> 2) * 8) + (((r0 >> 4) & 1) * 4) + (r0 & 3), p1 = (r1 & ~31) + (((r1 & 15) >> 2) * 8) + (((r1 >> 4) & 1) * 4) + (r1 & 3);
;   const unsigned bo0 = (unsigned)(p0 * ldb + c0), bo1 = (unsigned)(p1 * ldb + c1);
;   char* l0 = lds + tid * 16;
;     ...
;   bf16x8 At[4][2], Bq0[2][2], Bq1[2][2];
;   WAIT_V(0)
;   STAGE_B(0, 0, 0) STAGE_A(0, 0, 0) STAGE_B(0, 1, 0) STAGE_A(0, 1, 0)
;   if (wr == 1) BAR
	v_readfirstlane_b32 s2, v0
	s_nop 1
	v_lshl_or_b32 v140, s2, 6, v214
	s_nop 0
	v_bfe_i32 v2, v140, 27, 1
	v_lshlrev_b32_e32 v0, 4, v140
	v_lshrrev_b32_e32 v2, 22, v2
	v_add_u32_e32 v2, v0, v2
	v_and_b32_e32 v2, 0xfffffc00, v2
	v_sub_u32_e32 v2, v0, v2
	v_ashrrev_i32_e32 v1, 31, v140
	v_lshrrev_b32_e32 v3, 4, v2
	v_lshrrev_b32_e32 v1, 26, v1
	v_bitop3_b32 v3, v3, v2, 32 bitop3:0x6c
	v_ashrrev_i32_e32 v2, 31, v2
	v_add_u32_e32 v1, v140, v1
	v_lshrrev_b32_e32 v2, 26, v2
	v_ashrrev_i32_e32 v1, 6, v1
	v_add_u32_e32 v2, v3, v2
	v_lshlrev_b32_e32 v4, 3, v1
	v_ashrrev_i32_e32 v2, 6, v2
	v_lshlrev_b32_e32 v1, 5, v1
	v_and_b32_e32 v14, 32, v1
	v_mul_i32_i24_e32 v1, 64, v2
	v_sub_u32_e32 v1, v3, v1
	v_add_u32_e32 v3, 0x2000, v0
	v_ashrrev_i32_e32 v5, 31, v3
	v_lshrrev_b32_e32 v5, 22, v5
	v_add_u32_e32 v5, v3, v5
	v_ashrrev_i32_e32 v13, 10, v5
	v_mul_i32_i24_e32 v5, 0x400, v13
	v_sub_u32_e32 v3, v3, v5
	v_lshrrev_b32_e32 v5, 4, v3
	v_bitop3_b32 v3, v5, v3, 32 bitop3:0x6c
	v_ashrrev_i32_e32 v6, 31, v3
	v_lshrrev_b32_e32 v6, 26, v6
	v_and_b32_e32 v4, -16, v4
	v_ashrrev_i16_sdwa v15, v215, sext(v1) dst_sel:DWORD dst_unused:UNUSED_PAD src0_sel:DWORD src1_sel:BYTE_0
	v_lshlrev_b32_e32 v5, 3, v13
	v_add_u32_e32 v6, v3, v6
	v_add_u32_e32 v4, v2, v4
	v_add_u32_sdwa v1, v14, sext(v15) dst_sel:DWORD dst_unused:UNUSED_PAD src0_sel:DWORD src1_sel:WORD_0
	v_and_b32_e32 v5, -16, v5
	v_ashrrev_i32_e32 v16, 6, v6
	v_and_b32_e32 v6, 0xc0, v6
	v_add_u32_e32 v5, v16, v5
	v_sub_u32_e32 v3, v3, v6
	v_lshl_add_u32 v8, v4, 10, v1
	v_and_b32_e32 v19, 0xffffffe0, v4
	v_lshlrev_b32_e32 v6, 1, v4
	v_lshrrev_b32_e32 v4, 2, v4
	v_and_b32_e32 v22, 4, v4
	v_and_b32_e32 v24, 3, v2
	v_lshlrev_b32_e32 v4, 1, v5
	v_lshlrev_b32_e32 v7, 5, v13
	v_and_b32_e32 v21, 24, v6
	v_or_b32_e32 v2, v19, v24
	v_and_b32_e32 v20, 0xffffffe0, v5
	v_and_b32_e32 v23, 24, v4
	v_lshrrev_b32_e32 v4, 2, v5
	v_and_b32_e32 v26, 3, v16
	v_and_b32_e32 v17, 32, v7
	v_ashrrev_i16_sdwa v18, v215, sext(v3) dst_sel:DWORD dst_unused:UNUSED_PAD src0_sel:DWORD src1_sel:BYTE_0
	v_or3_b32 v2, v2, v21, v22
	v_and_b32_e32 v25, 4, v4
	v_or_b32_e32 v4, v20, v26
	v_add_u32_e32 v150, 0, v0
	v_add_u32_sdwa v3, v17, sext(v18) dst_sel:DWORD dst_unused:UNUSED_PAD src0_sel:DWORD src1_sel:WORD_0
	v_or3_b32 v4, v4, v23, v25
	v_lshl_add_u32 v64, v2, 10, v1
	v_add_u32_e32 v151, 0x10000, v150
	v_lshl_add_u32 v130, v5, 10, v3
	v_lshl_add_u32 v2, v4, 10, v3
	v_lshlrev_b64 v[6:7], 1, v[64:65]
	v_readfirstlane_b32 s2, v151
	v_mov_b32_e32 v3, v65
	v_add_u32_e32 v152, 0x12000, v150
	v_lshl_add_u64 v[0:1], s[22:23], 0, v[6:7]
	s_mov_b32 m0, s2
	v_lshlrev_b64 v[28:29], 1, v[2:3]
	v_readfirstlane_b32 s2, v152
	v_mov_b32_e32 v64, v8
	global_load_lds_dwordx4 v[0:1], off
	v_lshl_add_u64 v[2:3], s[22:23], 0, v[28:29]
	s_mov_b32 m0, s2
	v_lshlrev_b64 v[30:31], 1, v[64:65]
	v_readfirstlane_b32 s2, v150
	v_add_u32_e32 v153, 0x2000, v150
	global_load_lds_dwordx4 v[2:3], off
	v_lshl_add_u64 v[4:5], s[50:51], 0, v[30:31]
	s_mov_b32 m0, s2
	v_lshlrev_b64 v[32:33], 1, v[130:131]
	v_readfirstlane_b32 s2, v153
	v_add_u32_e32 v155, 0x14000, v150
	global_load_lds_dwordx4 v[4:5], off
	v_lshl_add_u64 v[8:9], s[50:51], 0, v[32:33]
	s_mov_b32 m0, s2
	v_readfirstlane_b32 s2, v155
	v_add_u32_e32 v156, 0x16000, v150
	global_load_lds_dwordx4 v[8:9], off
	v_lshl_add_u64 v[10:11], s[8:9], 0, v[6:7]
	s_mov_b32 m0, s2
	v_readfirstlane_b32 s2, v156
	v_add_u32_e32 v157, 0x4000, v150
	global_load_lds_dwordx4 v[10:11], off
	v_lshl_add_u64 v[6:7], s[8:9], 0, v[28:29]
	s_mov_b32 m0, s2
	v_readfirstlane_b32 s2, v157
	v_add_u32_e32 v158, 0x6000, v150
	global_load_lds_dwordx4 v[6:7], off
	v_lshl_add_u64 v[28:29], s[52:53], 0, v[30:31]
	s_mov_b32 m0, s2
	v_readfirstlane_b32 s2, v158
	global_load_lds_dwordx4 v[28:29], off
	v_lshl_add_u64 v[28:29], s[52:53], 0, v[32:33]
	s_mov_b32 m0, s2
	v_ashrrev_i32_e32 v12, 8, v140
	global_load_lds_dwordx4 v[28:29], off
	v_cmp_eq_u32_e32 vcc, 1, v12
	s_and_saveexec_b64 s[8:9], vcc
	s_cbranch_execz .LBB0_984
	s_barrier

; DI unsigned pk_bf16(float lo, float hi) { f32x2_t v = {lo, hi}; return __builtin_bit_cast(unsigned, __builtin_convertvector(v, bf16x2_t)); }
; DI float fsigmoid(float x) { return __builtin_amdgcn_rcpf(1.0f + __expf(-x)); }
; #define EPI_M _Pragma("unroll") for (int m = 0; m < 8; ++m)
; #define EPI_N _Pragma("unroll") for (int n = 0; n < 4; ++n)
; DI void p5_phase(const Params& p, char* lds) {
;     ...
;     EPI_IDX_N
;     EPI_M {
;       EPI_N {
;         u32x2 o; o[0] = pk_bf16(fsigmoid(ACC(m, n)[0]), fsigmoid(ACC(m, n)[1])); o[1] = pk_bf16(fsigmoid(ACC(m, n)[2]), fsigmoid(ACC(m, n)[3]));
;         tg[(m * 4 + n) * 512 + tid] = o;
;       }
;       __builtin_amdgcn_sched_barrier(0);
;     }
.LBB0_988:
	s_or_b64 exec, exec, s[8:9]
	s_waitcnt vmcnt(0)
	s_barrier
	s_getreg_b32 s2, hwreg(HW_REG_HW_ID, 0, 6)
	s_lshl_b32 s2, s2, 2
	s_and_b32 s2, s2, 0xfc
	s_add_i32 s2, s2, 0x20040
	v_mov_b32_e32 v64, s2
	ds_read_b32 v64, v64
	v_mul_f32_e32 v126, 0xbfb8aa3b, v126
	v_mul_f32_e32 v127, 0xbfb8aa3b, v127
	v_exp_f32_e32 v126, v126
	v_exp_f32_e32 v127, v127
	s_waitcnt lgkmcnt(0)
	v_readfirstlane_b32 s2, v64
	v_add_f32_e32 v64, 1.0, v126
	v_add_f32_e32 v126, 1.0, v127
	v_mul_f32_e32 v127, 0xbfb8aa3b, v128
	v_exp_f32_e32 v127, v127
	v_mul_f32_e32 v128, 0xbfb8aa3b, v129
	v_rcp_f32_e32 v64, v64
	v_exp_f32_e32 v128, v128
	v_rcp_f32_e32 v129, v126
	v_add_f32_e32 v126, 1.0, v127
	v_rcp_f32_e32 v127, v126
	v_add_f32_e32 v126, 1.0, v128
	v_cvt_pk_bf16_f32 v128, v64, v129
	v_mul_f32_e32 v64, 0xbfb8aa3b, v122
	v_mul_f32_e32 v122, 0xbfb8aa3b, v123
	v_exp_f32_e32 v64, v64
	v_exp_f32_e32 v122, v122
	v_mul_f32_e32 v123, 0xbfb8aa3b, v124
	v_exp_f32_e32 v123, v123
	v_mul_f32_e32 v124, 0xbfb8aa3b, v125
	v_rcp_f32_e32 v130, v126
	v_exp_f32_e32 v124, v124
	v_add_f32_e32 v64, 1.0, v64
	v_add_f32_e32 v122, 1.0, v122
	v_rcp_f32_e32 v64, v64
	v_rcp_f32_e32 v125, v122
	v_lshl_or_b32 v126, s2, 6, v214
	v_add_f32_e32 v122, 1.0, v123
	v_cvt_pk_bf16_f32 v129, v127, v130
	v_ashrrev_i32_e32 v127, 31, v126
	v_rcp_f32_e32 v130, v122
	v_add_f32_e32 v122, 1.0, v124
	v_rcp_f32_e32 v124, v122
	v_lshl_add_u64 v[122:123], v[126:127], 3, s[10:11]
	global_store_dwordx2 v[122:123], v[128:129], off sc0 sc1
	v_cvt_pk_bf16_f32 v122, v64, v125
	v_mul_f32_e32 v64, 0xbfb8aa3b, v118
	v_mul_f32_e32 v118, 0xbfb8aa3b, v119
	v_exp_f32_e32 v64, v64
	v_exp_f32_e32 v118, v118
	v_mul_f32_e32 v119, 0xbfb8aa3b, v120
	v_exp_f32_e32 v119, v119
	v_mul_f32_e32 v120, 0xbfb8aa3b, v121
	v_exp_f32_e32 v120, v120
	v_add_f32_e32 v64, 1.0, v64
	v_add_f32_e32 v118, 1.0, v118
	v_rcp_f32_e32 v64, v64
	v_rcp_f32_e32 v121, v118
	v_cvt_pk_bf16_f32 v123, v130, v124
	v_add_u32_e32 v124, 0x200, v126
	v_add_f32_e32 v118, 1.0, v119
	v_ashrrev_i32_e32 v125, 31, v124
	v_rcp_f32_e32 v127, v118
	v_add_f32_e32 v118, 1.0, v120
	v_rcp_f32_e32 v120, v118
	v_lshl_add_u64 v[118:119], v[124:125], 3, s[10:11]
	global_store_dwordx2 v[118:119], v[122:123], off sc0 sc1
	v_cvt_pk_bf16_f32 v118, v64, v121
	v_mul_f32_e32 v64, 0xbfb8aa3b, v114
	v_mul_f32_e32 v114, 0xbfb8aa3b, v115
	v_exp_f32_e32 v114, v114
	v_mul_f32_e32 v115, 0xbfb8aa3b, v116
	v_exp_f32_e32 v115, v115
	v_mul_f32_e32 v116, 0xbfb8aa3b, v117
	v_exp_f32_e32 v116, v116
	v_exp_f32_e32 v64, v64
	v_add_f32_e32 v114, 1.0, v114
	v_rcp_f32_e32 v117, v114
	v_add_f32_e32 v114, 1.0, v115
	v_rcp_f32_e32 v122, v114
	v_add_f32_e32 v114, 1.0, v116
	v_add_f32_e32 v64, 1.0, v64
	v_rcp_f32_e32 v116, v114
	v_cvt_pk_bf16_f32 v119, v127, v120
	v_add_u32_e32 v120, 0x400, v126
	v_rcp_f32_e32 v64, v64
	v_ashrrev_i32_e32 v121, 31, v120
	v_lshl_add_u64 v[114:115], v[120:121], 3, s[10:11]
	global_store_dwordx2 v[114:115], v[118:119], off sc0 sc1
	v_cvt_pk_bf16_f32 v115, v122, v116
	v_add_u32_e32 v116, 0x600, v126
	v_cvt_pk_bf16_f32 v114, v64, v117
	v_ashrrev_i32_e32 v117, 31, v116
	v_lshl_add_u64 v[116:117], v[116:117], 3, s[10:11]
	global_store_dwordx2 v[116:117], v[114:115], off sc0 sc1
	v_mul_f32_e32 v64, 0xbfb8aa3b, v110
	v_mul_f32_e32 v110, 0xbfb8aa3b, v111
	v_exp_f32_e32 v64, v64
	v_exp_f32_e32 v110, v110
	v_mul_f32_e32 v111, 0xbfb8aa3b, v112
	v_exp_f32_e32 v111, v111
	v_add_f32_e32 v64, 1.0, v64
	v_add_f32_e32 v110, 1.0, v110
	v_mul_f32_e32 v112, 0xbfb8aa3b, v113
	v_rcp_f32_e32 v64, v64
	v_exp_f32_e32 v112, v112
	v_rcp_f32_e32 v113, v110
	v_add_f32_e32 v110, 1.0, v111
	v_rcp_f32_e32 v111, v110
	v_add_f32_e32 v110, 1.0, v112
	v_cvt_pk_bf16_f32 v112, v64, v113
	v_mul_f32_e32 v64, 0xbfb8aa3b, v106
	v_mul_f32_e32 v106, 0xbfb8aa3b, v107
	v_exp_f32_e32 v64, v64
	v_exp_f32_e32 v106, v106
	v_mul_f32_e32 v107, 0xbfb8aa3b, v108
	v_exp_f32_e32 v107, v107
	v_mul_f32_e32 v108, 0xbfb8aa3b, v109
	v_rcp_f32_e32 v114, v110
	v_exp_f32_e32 v108, v108
	v_add_f32_e32 v64, 1.0, v64
	v_add_f32_e32 v106, 1.0, v106
	v_rcp_f32_e32 v64, v64
	v_rcp_f32_e32 v109, v106
	v_add_u32_e32 v110, 0x800, v126
	v_add_f32_e32 v106, 1.0, v107
	v_cvt_pk_bf16_f32 v113, v111, v114
	v_ashrrev_i32_e32 v111, 31, v110
	v_rcp_f32_e32 v114, v106
	v_add_f32_e32 v106, 1.0, v108
	v_rcp_f32_e32 v108, v106
	v_lshl_add_u64 v[106:107], v[110:111], 3, s[10:11]
	global_store_dwordx2 v[106:107], v[112:113], off sc0 sc1
	v_cvt_pk_bf16_f32 v106, v64, v109
	v_mul_f32_e32 v64, 0xbfb8aa3b, v102
	v_mul_f32_e32 v102, 0xbfb8aa3b, v103
	v_exp_f32_e32 v64, v64
	v_exp_f32_e32 v102, v102
	v_mul_f32_e32 v103, 0xbfb8aa3b, v104
	v_exp_f32_e32 v103, v103
	v_mul_f32_e32 v104, 0xbfb8aa3b, v105
	v_exp_f32_e32 v104, v104
	v_add_f32_e32 v64, 1.0, v64
	v_add_f32_e32 v102, 1.0, v102
	v_rcp_f32_e32 v64, v64
	v_rcp_f32_e32 v105, v102
	v_cvt_pk_bf16_f32 v107, v114, v108
	v_add_u32_e32 v108, 0xa00, v126
	v_add_f32_e32 v102, 1.0, v103
	v_ashrrev_i32_e32 v109, 31, v108
	v_rcp_f32_e32 v110, v102
	v_add_f32_e32 v102, 1.0, v104
	v_rcp_f32_e32 v104, v102
	v_lshl_add_u64 v[102:103], v[108:109], 3, s[10:11]
	global_store_dwordx2 v[102:103], v[106:107], off sc0 sc1
	v_cvt_pk_bf16_f32 v102, v64, v105
	v_mul_f32_e32 v64, 0xbfb8aa3b, v98
	v_mul_f32_e32 v98, 0xbfb8aa3b, v99
	v_exp_f32_e32 v98, v98
	v_mul_f32_e32 v99, 0xbfb8aa3b, v100
	v_exp_f32_e32 v99, v99
	v_mul_f32_e32 v100, 0xbfb8aa3b, v101
	v_exp_f32_e32 v100, v100
	v_exp_f32_e32 v64, v64
	v_add_f32_e32 v98, 1.0, v98
	v_rcp_f32_e32 v101, v98
	v_add_f32_e32 v98, 1.0, v99
	v_rcp_f32_e32 v106, v98
	v_add_f32_e32 v98, 1.0, v100
	v_add_f32_e32 v64, 1.0, v64
	v_rcp_f32_e32 v100, v98
	v_cvt_pk_bf16_f32 v103, v110, v104
	v_add_u32_e32 v104, 0xc00, v126
; DI unsigned pk_bf16(float lo, float hi) { f32x2_t v = {lo, hi}; return __builtin_bit_cast(unsigned, __builtin_convertvector(v, bf16x2_t)); }
; DI float fsigmoid(float x) { return __builtin_amdgcn_rcpf(1.0f + __expf(-x)); }
; #define EPI_M _Pragma("unroll") for (int m = 0; m < 8; ++m)
; #define EPI_N _Pragma("unroll") for (int n = 0; n < 4; ++n)
; DI void p5_phase(const Params& p, char* lds) {
;     ...
;     EPI_M {
;       EPI_N {
;         u32x2 o; o[0] = pk_bf16(fsigmoid(ACC(m, n)[0]), fsigmoid(ACC(m, n)[1])); o[1] = pk_bf16(fsigmoid(ACC(m, n)[2]), fsigmoid(ACC(m, n)[3]));
;         tg[(m * 4 + n) * 512 + tid] = o;
;       }
;       __builtin_amdgcn_sched_barrier(0);
	v_rcp_f32_e32 v64, v64
	v_ashrrev_i32_e32 v105, 31, v104
	v_lshl_add_u64 v[98:99], v[104:105], 3, s[10:11]
	global_store_dwordx2 v[98:99], v[102:103], off sc0 sc1
	v_cvt_pk_bf16_f32 v99, v106, v100
	v_add_u32_e32 v100, 0xe00, v126
	v_cvt_pk_bf16_f32 v98, v64, v101
	v_ashrrev_i32_e32 v101, 31, v100
	v_lshl_add_u64 v[100:101], v[100:101], 3, s[10:11]
	global_store_dwordx2 v[100:101], v[98:99], off sc0 sc1
	v_mul_f32_e32 v64, 0xbfb8aa3b, v94
	v_mul_f32_e32 v94, 0xbfb8aa3b, v95
	v_exp_f32_e32 v64, v64
	v_exp_f32_e32 v94, v94
	v_mul_f32_e32 v95, 0xbfb8aa3b, v96
	v_exp_f32_e32 v95, v95
	v_add_f32_e32 v64, 1.0, v64
	v_add_f32_e32 v94, 1.0, v94
	v_mul_f32_e32 v96, 0xbfb8aa3b, v97
	v_rcp_f32_e32 v64, v64
	v_exp_f32_e32 v96, v96
	v_rcp_f32_e32 v97, v94
	v_add_f32_e32 v94, 1.0, v95
	v_rcp_f32_e32 v95, v94
	v_add_f32_e32 v94, 1.0, v96
	v_cvt_pk_bf16_f32 v96, v64, v97
	v_mul_f32_e32 v64, 0xbfb8aa3b, v90
	v_mul_f32_e32 v90, 0xbfb8aa3b, v91
	v_exp_f32_e32 v64, v64
	v_exp_f32_e32 v90, v90
	v_mul_f32_e32 v91, 0xbfb8aa3b, v92
	v_exp_f32_e32 v91, v91
	v_mul_f32_e32 v92, 0xbfb8aa3b, v93
	v_rcp_f32_e32 v98, v94
	v_exp_f32_e32 v92, v92
	v_add_f32_e32 v64, 1.0, v64
	v_add_f32_e32 v90, 1.0, v90
	v_rcp_f32_e32 v64, v64
	v_rcp_f32_e32 v93, v90
	v_add_u32_e32 v94, 0x1000, v126
	v_add_f32_e32 v90, 1.0, v91
	v_cvt_pk_bf16_f32 v97, v95, v98
	v_ashrrev_i32_e32 v95, 31, v94
	v_rcp_f32_e32 v98, v90
	v_add_f32_e32 v90, 1.0, v92
	v_rcp_f32_e32 v92, v90
	v_lshl_add_u64 v[90:91], v[94:95], 3, s[10:11]
	global_store_dwordx2 v[90:91], v[96:97], off sc0 sc1
	v_cvt_pk_bf16_f32 v90, v64, v93
	v_mul_f32_e32 v64, 0xbfb8aa3b, v86
	v_mul_f32_e32 v86, 0xbfb8aa3b, v87
	v_exp_f32_e32 v64, v64
	v_exp_f32_e32 v86, v86
	v_mul_f32_e32 v87, 0xbfb8aa3b, v88
	v_exp_f32_e32 v87, v87
	v_mul_f32_e32 v88, 0xbfb8aa3b, v89
	v_exp_f32_e32 v88, v88
	v_add_f32_e32 v64, 1.0, v64
	v_add_f32_e32 v86, 1.0, v86
	v_rcp_f32_e32 v64, v64
	v_rcp_f32_e32 v89, v86
	v_cvt_pk_bf16_f32 v91, v98, v92
	v_add_u32_e32 v92, 0x1200, v126
	v_add_f32_e32 v86, 1.0, v87
	v_ashrrev_i32_e32 v93, 31, v92
	v_rcp_f32_e32 v94, v86
	v_add_f32_e32 v86, 1.0, v88
	v_rcp_f32_e32 v88, v86
	v_lshl_add_u64 v[86:87], v[92:93], 3, s[10:11]
	global_store_dwordx2 v[86:87], v[90:91], off sc0 sc1
	v_cvt_pk_bf16_f32 v86, v64, v89
	v_mul_f32_e32 v64, 0xbfb8aa3b, v82
	v_mul_f32_e32 v82, 0xbfb8aa3b, v83
	v_exp_f32_e32 v82, v82
	v_mul_f32_e32 v83, 0xbfb8aa3b, v84
	v_exp_f32_e32 v83, v83
	v_mul_f32_e32 v84, 0xbfb8aa3b, v85
	v_exp_f32_e32 v84, v84
	v_exp_f32_e32 v64, v64
	v_add_f32_e32 v82, 1.0, v82
	v_rcp_f32_e32 v85, v82
	v_add_f32_e32 v82, 1.0, v83
	v_rcp_f32_e32 v90, v82
	v_add_f32_e32 v82, 1.0, v84
	v_add_f32_e32 v64, 1.0, v64
	v_rcp_f32_e32 v84, v82
	v_cvt_pk_bf16_f32 v87, v94, v88
	v_add_u32_e32 v88, 0x1400, v126
	v_rcp_f32_e32 v64, v64
	v_ashrrev_i32_e32 v89, 31, v88
	v_lshl_add_u64 v[82:83], v[88:89], 3, s[10:11]
	global_store_dwordx2 v[82:83], v[86:87], off sc0 sc1
	v_cvt_pk_bf16_f32 v83, v90, v84
	v_add_u32_e32 v84, 0x1600, v126
	v_cvt_pk_bf16_f32 v82, v64, v85
	v_ashrrev_i32_e32 v85, 31, v84
	v_lshl_add_u64 v[84:85], v[84:85], 3, s[10:11]
	global_store_dwordx2 v[84:85], v[82:83], off sc0 sc1
	v_mul_f32_e32 v64, 0xbfb8aa3b, v78
	v_mul_f32_e32 v78, 0xbfb8aa3b, v79
	v_exp_f32_e32 v64, v64
	v_exp_f32_e32 v78, v78
	v_mul_f32_e32 v79, 0xbfb8aa3b, v80
	v_exp_f32_e32 v79, v79
	v_add_f32_e32 v64, 1.0, v64
	v_add_f32_e32 v78, 1.0, v78
	v_mul_f32_e32 v80, 0xbfb8aa3b, v81
	v_rcp_f32_e32 v64, v64
	v_exp_f32_e32 v80, v80
	v_rcp_f32_e32 v81, v78
	v_add_f32_e32 v78, 1.0, v79
	v_rcp_f32_e32 v79, v78
	v_add_f32_e32 v78, 1.0, v80
	v_cvt_pk_bf16_f32 v80, v64, v81
	v_mul_f32_e32 v64, 0xbfb8aa3b, v74
	v_mul_f32_e32 v74, 0xbfb8aa3b, v75
	v_exp_f32_e32 v64, v64
	v_exp_f32_e32 v74, v74
	v_mul_f32_e32 v75, 0xbfb8aa3b, v76
	v_exp_f32_e32 v75, v75
	v_mul_f32_e32 v76, 0xbfb8aa3b, v77
	v_rcp_f32_e32 v82, v78
	v_exp_f32_e32 v76, v76
	v_add_f32_e32 v64, 1.0, v64
	v_add_f32_e32 v74, 1.0, v74
	v_rcp_f32_e32 v64, v64
	v_rcp_f32_e32 v77, v74
	v_add_u32_e32 v78, 0x1800, v126
	v_add_f32_e32 v74, 1.0, v75
	v_cvt_pk_bf16_f32 v81, v79, v82
	v_ashrrev_i32_e32 v79, 31, v78
	v_rcp_f32_e32 v82, v74
	v_add_f32_e32 v74, 1.0, v76
	v_rcp_f32_e32 v76, v74
	v_lshl_add_u64 v[74:75], v[78:79], 3, s[10:11]
	global_store_dwordx2 v[74:75], v[80:81], off sc0 sc1
	v_cvt_pk_bf16_f32 v74, v64, v77
	v_mul_f32_e32 v64, 0xbfb8aa3b, v70
	v_mul_f32_e32 v70, 0xbfb8aa3b, v71
	v_exp_f32_e32 v64, v64
	v_exp_f32_e32 v70, v70
	v_mul_f32_e32 v71, 0xbfb8aa3b, v72
	v_exp_f32_e32 v71, v71
	v_mul_f32_e32 v72, 0xbfb8aa3b, v73
	v_exp_f32_e32 v72, v72
	v_add_f32_e32 v64, 1.0, v64
	v_add_f32_e32 v70, 1.0, v70
	v_rcp_f32_e32 v64, v64
	v_rcp_f32_e32 v73, v70
	v_cvt_pk_bf16_f32 v75, v82, v76
	v_add_u32_e32 v76, 0x1a00, v126
	v_add_f32_e32 v70, 1.0, v71
	v_ashrrev_i32_e32 v77, 31, v76
	v_rcp_f32_e32 v78, v70
	v_add_f32_e32 v70, 1.0, v72
	v_rcp_f32_e32 v72, v70
	v_lshl_add_u64 v[70:71], v[76:77], 3, s[10:11]
	global_store_dwordx2 v[70:71], v[74:75], off sc0 sc1
	v_cvt_pk_bf16_f32 v70, v64, v73
	v_mul_f32_e32 v64, 0xbfb8aa3b, v66
	v_mul_f32_e32 v66, 0xbfb8aa3b, v67
	v_exp_f32_e32 v66, v66
	v_mul_f32_e32 v67, 0xbfb8aa3b, v68
	v_exp_f32_e32 v67, v67
	v_mul_f32_e32 v68, 0xbfb8aa3b, v69
	v_exp_f32_e32 v68, v68
	v_exp_f32_e32 v64, v64
	v_add_f32_e32 v66, 1.0, v66
	v_rcp_f32_e32 v69, v66
	v_add_f32_e32 v66, 1.0, v67
	v_rcp_f32_e32 v74, v66
	v_add_f32_e32 v66, 1.0, v68
	v_add_f32_e32 v64, 1.0, v64
	v_rcp_f32_e32 v68, v66
	v_cvt_pk_bf16_f32 v71, v78, v72
	v_add_u32_e32 v72, 0x1c00, v126
	v_rcp_f32_e32 v64, v64
	v_ashrrev_i32_e32 v73, 31, v72
	v_lshl_add_u64 v[66:67], v[72:73], 3, s[10:11]
	global_store_dwordx2 v[66:67], v[70:71], off sc0 sc1
; DI unsigned pk_bf16(float lo, float hi) { f32x2_t v = {lo, hi}; return __builtin_bit_cast(unsigned, __builtin_convertvector(v, bf16x2_t)); }
; DI float fsigmoid(float x) { return __builtin_amdgcn_rcpf(1.0f + __expf(-x)); }
; #define EPI_M _Pragma("unroll") for (int m = 0; m < 8; ++m)
; #define EPI_N _Pragma("unroll") for (int n = 0; n < 4; ++n)
; DI void p5_phase(const Params& p, char* lds) {
;     ...
;     EPI_M {
;       EPI_N {
;         u32x2 o; o[0] = pk_bf16(fsigmoid(ACC(m, n)[0]), fsigmoid(ACC(m, n)[1])); o[1] = pk_bf16(fsigmoid(ACC(m, n)[2]), fsigmoid(ACC(m, n)[3]));
;         tg[(m * 4 + n) * 512 + tid] = o;
;       }
;       __builtin_amdgcn_sched_barrier(0);
;     }
	v_cvt_pk_bf16_f32 v67, v74, v68
	v_add_u32_e32 v68, 0x1e00, v126
	v_cvt_pk_bf16_f32 v66, v64, v69
	v_ashrrev_i32_e32 v69, 31, v68
	v_lshl_add_u64 v[68:69], v[68:69], 3, s[10:11]
	global_store_dwordx2 v[68:69], v[66:67], off sc0 sc1
	v_mul_f32_e32 v60, 0xbfb8aa3b, v60
	v_exp_f32_e32 v60, v60
	v_mul_f32_e32 v61, 0xbfb8aa3b, v61
	v_exp_f32_e32 v61, v61
	v_mul_f32_e32 v56, 0xbfb8aa3b, v56
	v_add_f32_e32 v60, 1.0, v60
	v_rcp_f32_e32 v64, v60
	v_mul_f32_e32 v60, 0xbfb8aa3b, v62
	v_add_f32_e32 v61, 1.0, v61
	v_exp_f32_e32 v60, v60
	v_mul_f32_e32 v62, 0xbfb8aa3b, v63
	v_exp_f32_e32 v56, v56
	v_mul_f32_e32 v57, 0xbfb8aa3b, v57
	v_exp_f32_e32 v62, v62
	v_rcp_f32_e32 v61, v61
	v_exp_f32_e32 v57, v57
	v_add_f32_e32 v60, 1.0, v60
	v_add_f32_e32 v56, 1.0, v56
	v_rcp_f32_e32 v63, v60
	v_add_f32_e32 v60, 1.0, v62
	v_cvt_pk_bf16_f32 v62, v64, v61
	v_rcp_f32_e32 v64, v56
	v_add_f32_e32 v56, 1.0, v57
	v_mul_f32_e32 v57, 0xbfb8aa3b, v58
	v_exp_f32_e32 v57, v57
	v_mul_f32_e32 v58, 0xbfb8aa3b, v59
	v_mul_f32_e32 v52, 0xbfb8aa3b, v52
	v_rcp_f32_e32 v66, v60
	v_exp_f32_e32 v58, v58
	v_exp_f32_e32 v52, v52
	v_mul_f32_e32 v53, 0xbfb8aa3b, v53
	v_exp_f32_e32 v53, v53
	v_add_u32_e32 v60, 0x2000, v126
	v_rcp_f32_e32 v59, v56
	v_add_f32_e32 v56, 1.0, v57
	v_cvt_pk_bf16_f32 v63, v63, v66
	v_ashrrev_i32_e32 v61, 31, v60
	v_rcp_f32_e32 v66, v56
	v_add_f32_e32 v56, 1.0, v58
	v_add_f32_e32 v52, 1.0, v52
	v_rcp_f32_e32 v58, v56
	v_lshl_add_u64 v[56:57], v[60:61], 3, s[10:11]
	v_rcp_f32_e32 v60, v52
	v_add_f32_e32 v52, 1.0, v53
	v_mul_f32_e32 v53, 0xbfb8aa3b, v54
	v_exp_f32_e32 v53, v53
	v_mul_f32_e32 v54, 0xbfb8aa3b, v55
	v_exp_f32_e32 v54, v54
	v_mul_f32_e32 v48, 0xbfb8aa3b, v48
	v_exp_f32_e32 v48, v48
	v_mul_f32_e32 v49, 0xbfb8aa3b, v49
	v_exp_f32_e32 v49, v49
	global_store_dwordx2 v[56:57], v[62:63], off sc0 sc1
	v_cvt_pk_bf16_f32 v57, v66, v58
	v_add_u32_e32 v58, 0x2200, v126
	v_rcp_f32_e32 v55, v52
	v_add_f32_e32 v52, 1.0, v53
	v_cvt_pk_bf16_f32 v56, v64, v59
	v_ashrrev_i32_e32 v59, 31, v58
	v_rcp_f32_e32 v61, v52
	v_add_f32_e32 v52, 1.0, v54
	v_rcp_f32_e32 v54, v52
	v_lshl_add_u64 v[52:53], v[58:59], 3, s[10:11]
	v_add_f32_e32 v48, 1.0, v48
	global_store_dwordx2 v[52:53], v[56:57], off sc0 sc1
	v_rcp_f32_e32 v56, v48
	v_add_f32_e32 v48, 1.0, v49
	v_mul_f32_e32 v49, 0xbfb8aa3b, v50
	v_exp_f32_e32 v49, v49
	v_mul_f32_e32 v50, 0xbfb8aa3b, v51
	v_exp_f32_e32 v50, v50
	v_rcp_f32_e32 v51, v48
	v_add_f32_e32 v48, 1.0, v49
	v_rcp_f32_e32 v57, v48
	v_add_f32_e32 v48, 1.0, v50
	v_rcp_f32_e32 v50, v48
	v_cvt_pk_bf16_f32 v53, v61, v54
	v_add_u32_e32 v54, 0x2400, v126
	v_cvt_pk_bf16_f32 v52, v60, v55
	v_ashrrev_i32_e32 v55, 31, v54
	v_lshl_add_u64 v[48:49], v[54:55], 3, s[10:11]
	global_store_dwordx2 v[48:49], v[52:53], off sc0 sc1
	v_cvt_pk_bf16_f32 v49, v57, v50
	v_add_u32_e32 v50, 0x2600, v126
	v_cvt_pk_bf16_f32 v48, v56, v51
	v_ashrrev_i32_e32 v51, 31, v50
	v_lshl_add_u64 v[50:51], v[50:51], 3, s[10:11]
	global_store_dwordx2 v[50:51], v[48:49], off sc0 sc1
	v_mul_f32_e32 v44, 0xbfb8aa3b, v44
	v_exp_f32_e32 v44, v44
	v_mul_f32_e32 v45, 0xbfb8aa3b, v45
	v_exp_f32_e32 v45, v45
	v_mul_f32_e32 v40, 0xbfb8aa3b, v40
	v_add_f32_e32 v44, 1.0, v44
	v_rcp_f32_e32 v48, v44
	v_mul_f32_e32 v44, 0xbfb8aa3b, v46
	v_add_f32_e32 v45, 1.0, v45
	v_exp_f32_e32 v44, v44
	v_mul_f32_e32 v46, 0xbfb8aa3b, v47
	v_exp_f32_e32 v40, v40
	v_mul_f32_e32 v41, 0xbfb8aa3b, v41
	v_exp_f32_e32 v46, v46
	v_rcp_f32_e32 v45, v45
	v_exp_f32_e32 v41, v41
	v_add_f32_e32 v44, 1.0, v44
	v_add_f32_e32 v40, 1.0, v40
	v_rcp_f32_e32 v47, v44
	v_add_f32_e32 v44, 1.0, v46
	v_cvt_pk_bf16_f32 v46, v48, v45
	v_rcp_f32_e32 v48, v40
	v_add_f32_e32 v40, 1.0, v41
	v_mul_f32_e32 v41, 0xbfb8aa3b, v42
	v_exp_f32_e32 v41, v41
	v_mul_f32_e32 v42, 0xbfb8aa3b, v43
	v_mul_f32_e32 v36, 0xbfb8aa3b, v36
	v_rcp_f32_e32 v49, v44
	v_exp_f32_e32 v42, v42
	v_exp_f32_e32 v36, v36
	v_mul_f32_e32 v37, 0xbfb8aa3b, v37
	v_exp_f32_e32 v37, v37
	v_add_u32_e32 v44, 0x2800, v126
	v_rcp_f32_e32 v43, v40
	v_add_f32_e32 v40, 1.0, v41
	v_cvt_pk_bf16_f32 v47, v47, v49
	v_ashrrev_i32_e32 v45, 31, v44
	v_rcp_f32_e32 v49, v40
	v_add_f32_e32 v40, 1.0, v42
	v_add_f32_e32 v36, 1.0, v36
	v_rcp_f32_e32 v42, v40
	v_lshl_add_u64 v[40:41], v[44:45], 3, s[10:11]
	v_rcp_f32_e32 v44, v36
	v_add_f32_e32 v36, 1.0, v37
	v_mul_f32_e32 v37, 0xbfb8aa3b, v38
	v_exp_f32_e32 v37, v37
	v_mul_f32_e32 v38, 0xbfb8aa3b, v39
	v_exp_f32_e32 v38, v38
	v_mul_f32_e32 v32, 0xbfb8aa3b, v32
	v_exp_f32_e32 v32, v32
	v_mul_f32_e32 v33, 0xbfb8aa3b, v33
	v_exp_f32_e32 v33, v33
	global_store_dwordx2 v[40:41], v[46:47], off sc0 sc1
	v_cvt_pk_bf16_f32 v41, v49, v42
	v_add_u32_e32 v42, 0x2a00, v126
	v_rcp_f32_e32 v39, v36
	v_add_f32_e32 v36, 1.0, v37
	v_cvt_pk_bf16_f32 v40, v48, v43
	v_ashrrev_i32_e32 v43, 31, v42
	v_rcp_f32_e32 v45, v36
	v_add_f32_e32 v36, 1.0, v38
	v_rcp_f32_e32 v38, v36
	v_lshl_add_u64 v[36:37], v[42:43], 3, s[10:11]
	v_add_f32_e32 v32, 1.0, v32
	global_store_dwordx2 v[36:37], v[40:41], off sc0 sc1
	v_rcp_f32_e32 v40, v32
	v_add_f32_e32 v32, 1.0, v33
	v_mul_f32_e32 v33, 0xbfb8aa3b, v34
	v_exp_f32_e32 v33, v33
	v_mul_f32_e32 v34, 0xbfb8aa3b, v35
	v_exp_f32_e32 v34, v34
	v_rcp_f32_e32 v35, v32
	v_add_f32_e32 v32, 1.0, v33
	v_rcp_f32_e32 v41, v32
	v_add_f32_e32 v32, 1.0, v34
	v_rcp_f32_e32 v34, v32
	v_cvt_pk_bf16_f32 v37, v45, v38
	v_add_u32_e32 v38, 0x2c00, v126
	v_cvt_pk_bf16_f32 v36, v44, v39
	v_ashrrev_i32_e32 v39, 31, v38
	v_lshl_add_u64 v[32:33], v[38:39], 3, s[10:11]
	global_store_dwordx2 v[32:33], v[36:37], off sc0 sc1
	v_cvt_pk_bf16_f32 v33, v41, v34
	v_add_u32_e32 v34, 0x2e00, v126
	v_cvt_pk_bf16_f32 v32, v40, v35
	v_ashrrev_i32_e32 v35, 31, v34
	v_lshl_add_u64 v[34:35], v[34:35], 3, s[10:11]
; DI unsigned pk_bf16(float lo, float hi) { f32x2_t v = {lo, hi}; return __builtin_bit_cast(unsigned, __builtin_convertvector(v, bf16x2_t)); }
; DI float fsigmoid(float x) { return __builtin_amdgcn_rcpf(1.0f + __expf(-x)); }
; #define EPI_M _Pragma("unroll") for (int m = 0; m < 8; ++m)
; #define EPI_N _Pragma("unroll") for (int n = 0; n < 4; ++n)
; DI void p5_phase(const Params& p, char* lds) {
;     ...
;     EPI_M {
;       EPI_N {
;         u32x2 o; o[0] = pk_bf16(fsigmoid(ACC(m, n)[0]), fsigmoid(ACC(m, n)[1])); o[1] = pk_bf16(fsigmoid(ACC(m, n)[2]), fsigmoid(ACC(m, n)[3]));
;         tg[(m * 4 + n) * 512 + tid] = o;
;       }
;       __builtin_amdgcn_sched_barrier(0);
;     }
	global_store_dwordx2 v[34:35], v[32:33], off sc0 sc1
	v_mul_f32_e32 v28, 0xbfb8aa3b, v28
	v_exp_f32_e32 v28, v28
	v_mul_f32_e32 v29, 0xbfb8aa3b, v29
	v_exp_f32_e32 v29, v29
	v_mul_f32_e32 v24, 0xbfb8aa3b, v24
	v_add_f32_e32 v28, 1.0, v28
	v_rcp_f32_e32 v32, v28
	v_mul_f32_e32 v28, 0xbfb8aa3b, v30
	v_add_f32_e32 v29, 1.0, v29
	v_exp_f32_e32 v28, v28
	v_mul_f32_e32 v30, 0xbfb8aa3b, v31
	v_exp_f32_e32 v24, v24
	v_mul_f32_e32 v25, 0xbfb8aa3b, v25
	v_exp_f32_e32 v30, v30
	v_rcp_f32_e32 v29, v29
	v_exp_f32_e32 v25, v25
	v_add_f32_e32 v28, 1.0, v28
	v_add_f32_e32 v24, 1.0, v24
	v_rcp_f32_e32 v31, v28
	v_add_f32_e32 v28, 1.0, v30
	v_cvt_pk_bf16_f32 v30, v32, v29
	v_rcp_f32_e32 v32, v24
	v_add_f32_e32 v24, 1.0, v25
	v_mul_f32_e32 v25, 0xbfb8aa3b, v26
	v_exp_f32_e32 v25, v25
	v_mul_f32_e32 v26, 0xbfb8aa3b, v27
	v_mul_f32_e32 v20, 0xbfb8aa3b, v20
	v_rcp_f32_e32 v33, v28
	v_exp_f32_e32 v26, v26
	v_exp_f32_e32 v20, v20
	v_mul_f32_e32 v21, 0xbfb8aa3b, v21
	v_exp_f32_e32 v21, v21
	v_add_u32_e32 v28, 0x3000, v126
	v_rcp_f32_e32 v27, v24
	v_add_f32_e32 v24, 1.0, v25
	v_cvt_pk_bf16_f32 v31, v31, v33
	v_ashrrev_i32_e32 v29, 31, v28
	v_rcp_f32_e32 v33, v24
	v_add_f32_e32 v24, 1.0, v26
	v_add_f32_e32 v20, 1.0, v20
	v_rcp_f32_e32 v26, v24
	v_lshl_add_u64 v[24:25], v[28:29], 3, s[10:11]
	v_rcp_f32_e32 v28, v20
	v_add_f32_e32 v20, 1.0, v21
	v_mul_f32_e32 v21, 0xbfb8aa3b, v22
	v_exp_f32_e32 v21, v21
	v_mul_f32_e32 v22, 0xbfb8aa3b, v23
	v_exp_f32_e32 v22, v22
	v_mul_f32_e32 v16, 0xbfb8aa3b, v16
	v_exp_f32_e32 v16, v16
	v_mul_f32_e32 v17, 0xbfb8aa3b, v17
	v_exp_f32_e32 v17, v17
	global_store_dwordx2 v[24:25], v[30:31], off sc0 sc1
	v_cvt_pk_bf16_f32 v25, v33, v26
	v_add_u32_e32 v26, 0x3200, v126
	v_rcp_f32_e32 v23, v20
	v_add_f32_e32 v20, 1.0, v21
	v_cvt_pk_bf16_f32 v24, v32, v27
	v_ashrrev_i32_e32 v27, 31, v26
	v_rcp_f32_e32 v29, v20
	v_add_f32_e32 v20, 1.0, v22
	v_rcp_f32_e32 v22, v20
	v_lshl_add_u64 v[20:21], v[26:27], 3, s[10:11]
	v_add_f32_e32 v16, 1.0, v16
	global_store_dwordx2 v[20:21], v[24:25], off sc0 sc1
	v_rcp_f32_e32 v24, v16
	v_add_f32_e32 v16, 1.0, v17
	v_mul_f32_e32 v17, 0xbfb8aa3b, v18
	v_exp_f32_e32 v17, v17
	v_mul_f32_e32 v18, 0xbfb8aa3b, v19
	v_exp_f32_e32 v18, v18
	v_rcp_f32_e32 v19, v16
	v_add_f32_e32 v16, 1.0, v17
	v_rcp_f32_e32 v25, v16
	v_add_f32_e32 v16, 1.0, v18
	v_rcp_f32_e32 v18, v16
	v_cvt_pk_bf16_f32 v21, v29, v22
	v_add_u32_e32 v22, 0x3400, v126
	v_cvt_pk_bf16_f32 v20, v28, v23
	v_ashrrev_i32_e32 v23, 31, v22
	v_lshl_add_u64 v[16:17], v[22:23], 3, s[10:11]
	global_store_dwordx2 v[16:17], v[20:21], off sc0 sc1
	v_cvt_pk_bf16_f32 v17, v25, v18
	v_add_u32_e32 v18, 0x3600, v126
	v_cvt_pk_bf16_f32 v16, v24, v19
	v_ashrrev_i32_e32 v19, 31, v18
	v_lshl_add_u64 v[18:19], v[18:19], 3, s[10:11]
	global_store_dwordx2 v[18:19], v[16:17], off sc0 sc1
	v_mul_f32_e32 v12, 0xbfb8aa3b, v12
	v_exp_f32_e32 v12, v12
	v_mul_f32_e32 v13, 0xbfb8aa3b, v13
	v_exp_f32_e32 v13, v13
	v_mul_f32_e32 v8, 0xbfb8aa3b, v8
	v_add_f32_e32 v12, 1.0, v12
	v_rcp_f32_e32 v16, v12
	v_mul_f32_e32 v12, 0xbfb8aa3b, v14
	v_add_f32_e32 v13, 1.0, v13
	v_exp_f32_e32 v12, v12
	v_mul_f32_e32 v14, 0xbfb8aa3b, v15
	v_exp_f32_e32 v8, v8
	v_mul_f32_e32 v9, 0xbfb8aa3b, v9
	v_exp_f32_e32 v14, v14
	v_rcp_f32_e32 v13, v13
	v_exp_f32_e32 v9, v9
	v_add_f32_e32 v12, 1.0, v12
	v_add_f32_e32 v8, 1.0, v8
	v_rcp_f32_e32 v15, v12
	v_add_f32_e32 v12, 1.0, v14
	v_cvt_pk_bf16_f32 v14, v16, v13
	v_rcp_f32_e32 v16, v8
	v_add_f32_e32 v8, 1.0, v9
	v_mul_f32_e32 v9, 0xbfb8aa3b, v10
	v_exp_f32_e32 v9, v9
	v_mul_f32_e32 v10, 0xbfb8aa3b, v11
	v_mul_f32_e32 v4, 0xbfb8aa3b, v4
	v_rcp_f32_e32 v17, v12
	v_exp_f32_e32 v10, v10
	v_exp_f32_e32 v4, v4
	v_mul_f32_e32 v5, 0xbfb8aa3b, v5
	v_exp_f32_e32 v5, v5
	v_add_u32_e32 v12, 0x3800, v126
	v_rcp_f32_e32 v11, v8
	v_add_f32_e32 v8, 1.0, v9
	v_cvt_pk_bf16_f32 v15, v15, v17
	v_ashrrev_i32_e32 v13, 31, v12
	v_rcp_f32_e32 v17, v8
	v_add_f32_e32 v8, 1.0, v10
	v_add_f32_e32 v4, 1.0, v4
	v_rcp_f32_e32 v10, v8
	v_lshl_add_u64 v[8:9], v[12:13], 3, s[10:11]
	v_rcp_f32_e32 v12, v4
	v_add_f32_e32 v4, 1.0, v5
	v_mul_f32_e32 v5, 0xbfb8aa3b, v6
	v_exp_f32_e32 v5, v5
	v_mul_f32_e32 v6, 0xbfb8aa3b, v7
	v_exp_f32_e32 v6, v6
	v_mul_f32_e32 v0, 0xbfb8aa3b, v0
	v_exp_f32_e32 v0, v0
	v_mul_f32_e32 v1, 0xbfb8aa3b, v1
	v_exp_f32_e32 v1, v1
	global_store_dwordx2 v[8:9], v[14:15], off sc0 sc1
	v_cvt_pk_bf16_f32 v9, v17, v10
	v_add_u32_e32 v10, 0x3a00, v126
	v_rcp_f32_e32 v7, v4
	v_add_f32_e32 v4, 1.0, v5
	v_cvt_pk_bf16_f32 v8, v16, v11
	v_ashrrev_i32_e32 v11, 31, v10
	v_rcp_f32_e32 v13, v4
	v_add_f32_e32 v4, 1.0, v6
	v_rcp_f32_e32 v6, v4
	v_lshl_add_u64 v[4:5], v[10:11], 3, s[10:11]
	v_add_f32_e32 v0, 1.0, v0
	global_store_dwordx2 v[4:5], v[8:9], off sc0 sc1
	v_rcp_f32_e32 v8, v0
	v_add_f32_e32 v0, 1.0, v1
	v_mul_f32_e32 v1, 0xbfb8aa3b, v2
	v_exp_f32_e32 v1, v1
	v_mul_f32_e32 v2, 0xbfb8aa3b, v3
	v_exp_f32_e32 v2, v2
	v_rcp_f32_e32 v3, v0
	v_add_f32_e32 v0, 1.0, v1
	v_rcp_f32_e32 v9, v0
	v_add_f32_e32 v0, 1.0, v2
	v_rcp_f32_e32 v2, v0
	v_cvt_pk_bf16_f32 v5, v13, v6
	v_add_u32_e32 v6, 0x3c00, v126
	v_cvt_pk_bf16_f32 v4, v12, v7
	v_ashrrev_i32_e32 v7, 31, v6
	v_lshl_add_u64 v[0:1], v[6:7], 3, s[10:11]
	global_store_dwordx2 v[0:1], v[4:5], off sc0 sc1
	v_cvt_pk_bf16_f32 v1, v9, v2
	v_add_u32_e32 v2, 0x3e00, v126
	v_cvt_pk_bf16_f32 v0, v8, v3
	v_ashrrev_i32_e32 v3, 31, v2
	v_lshl_add_u64 v[2:3], v[2:3], 3, s[10:11]
	global_store_dwordx2 v[2:3], v[0:1], off sc0 sc1
	s_lshl_b64 s[2:3], s[58:59], 1
	s_add_u32 s22, s94, s2
	s_addc_u32 s23, s95, s3
	s_lshl_b64 s[2:3], s[56:57], 1
	s_add_u32 s8, s94, s2
	s_getreg_b32 s2, hwreg(HW_REG_HW_ID, 0, 6)
	s_addc_u32 s9, s95, s3
	s_lshl_b32 s2, s2, 2
	s_and_b32 s2, s2, 0xfc
	s_add_i32 s2, s2, 0x20040
	v_mov_b32_e32 v0, s2
	ds_read_b32 v0, v0
	v_mov_b32_e32 v131, v65
	s_waitcnt lgkmcnt(0)
; DI int my_tid() { int t = tid_raw(); asm volatile("" : "+v"(t)); return t; }
; #define STAGE_A(b, h, kt) { const u16* ap_ = A + (size_t)((h) * ahalf + (unsigned)(kt) * 64u); glds16(ap_ + ao0, l0 + SA_(b, h)); glds16(ap_ + ao1, l0 + SA_(b, h) + 8192); }
; #define STAGE_B(b, h, kt) { const u16* bp_ = ((h) ? B1 : B0) + (unsigned)(kt) * 64u; glds16(bp_ + bo0, l0 + SB_(b, h)); glds16(bp_ + bo1, l0 + SB_(b, h) + 8192); }
; #define WAIT_V(n) asm volatile("s_waitcnt vmcnt(" #n ")" ::: "memory");
; #define BAR __builtin_amdgcn_s_barrier();
; DI void gemm256(const u16* __restrict__ A, int lda, const u16* __restrict__ B0, const u16* __restrict__ B1, int ldb, int nt, acc_t& acc, char* lds) {
;   const int tid = my_tid();
;   const int lane = tid & 63, wid = tid >> 6, wr = wid >> 2, wc = wid & 3, fr = lane & 15, fq = lane >> 4;
;   int r0, c0, r1, c1;
;   stage_rc(tid * 16, r0, c0); stage_rc(tid * 16 + 8192, r1, c1);
;   const unsigned ao0 = (unsigned)(r0 * lda + c0), ao1 = (unsigned)(r1 * lda + c1);
;   const unsigned ahalf = 128u * (unsigned)lda;
;   const int p0 = (r0 & ~31) + (((r0 & 15) >> 2) * 8) + (((r0 >> 4) & 1) * 4) + (r0 & 3), p1 = (r1 & ~31) + (((r1 & 15) >> 2) * 8) + (((r1 >> 4) & 1) * 4) + (r1 & 3);
;   const unsigned bo0 = (unsigned)(p0 * ldb + c0), bo1 = (unsigned)(p1 * ldb + c1);
;   char* l0 = lds + tid * 16;
;     ...
;   bf16x8 At[4][2], Bq0[2][2], Bq1[2][2];
;   WAIT_V(0)
;   STAGE_B(0, 0, 0) STAGE_A(0, 0, 0) STAGE_B(0, 1, 0) STAGE_A(0, 1, 0)
;   if (wr == 1) BAR
	v_readfirstlane_b32 s2, v0
	s_nop 1
	v_lshl_or_b32 v140, s2, 6, v214
	s_nop 0
	v_ashrrev_i32_e32 v1, 31, v140
	v_lshrrev_b32_e32 v1, 26, v1
	v_add_u32_e32 v1, v140, v1
	v_ashrrev_i32_e32 v12, 6, v1
	v_bfe_i32 v1, v140, 27, 1
	v_lshlrev_b32_e32 v0, 4, v140
	v_lshrrev_b32_e32 v1, 22, v1
	v_add_u32_e32 v1, v0, v1
	v_and_b32_e32 v1, 0xfffffc00, v1
	v_sub_u32_e32 v1, v0, v1
	v_lshrrev_b32_e32 v2, 4, v1
	v_bitop3_b32 v2, v2, v1, 32 bitop3:0x6c
	v_ashrrev_i32_e32 v1, 31, v1
	v_lshrrev_b32_e32 v1, 26, v1
	v_lshlrev_b32_e32 v3, 3, v12
	v_add_u32_e32 v1, v2, v1
	v_and_b32_e32 v3, -16, v3
	v_ashrrev_i32_e32 v16, 6, v1
	v_add_u32_e32 v1, v16, v3
	v_lshlrev_b32_e32 v3, 5, v12
	v_and_b32_e32 v14, 32, v3
	v_mul_i32_i24_e32 v3, 64, v16
	v_sub_u32_e32 v2, v2, v3
	v_add_u32_e32 v3, 0x2000, v0
	v_ashrrev_i32_e32 v4, 31, v3
	v_lshrrev_b32_e32 v4, 22, v4
	v_add_u32_e32 v4, v3, v4
	v_ashrrev_i32_e32 v19, 10, v4
	v_mul_i32_i24_e32 v4, 0x400, v19
	v_sub_u32_e32 v3, v3, v4
	v_lshrrev_b32_e32 v4, 4, v3
	v_bitop3_b32 v3, v4, v3, 32 bitop3:0x6c
	v_ashrrev_i32_e32 v5, 31, v3
	v_lshrrev_b32_e32 v5, 26, v5
	v_add_u32_e32 v5, v3, v5
	v_ashrrev_i32_e32 v25, 6, v5
	v_and_b32_e32 v5, 0xc0, v5
	v_ashrrev_i16_sdwa v15, v215, sext(v2) dst_sel:DWORD dst_unused:UNUSED_PAD src0_sel:DWORD src1_sel:BYTE_0
	v_lshlrev_b32_e32 v4, 3, v19
	v_lshlrev_b32_e32 v6, 5, v19
	v_sub_u32_e32 v3, v3, v5
	v_add_u32_sdwa v2, v14, sext(v15) dst_sel:DWORD dst_unused:UNUSED_PAD src0_sel:DWORD src1_sel:WORD_0
	v_and_b32_e32 v4, -16, v4
	v_and_b32_e32 v17, 32, v6
	v_ashrrev_i16_sdwa v18, v215, sext(v3) dst_sel:DWORD dst_unused:UNUSED_PAD src0_sel:DWORD src1_sel:BYTE_0
	v_add_u32_e32 v4, v25, v4
	v_add_u32_sdwa v3, v17, sext(v18) dst_sel:DWORD dst_unused:UNUSED_PAD src0_sel:DWORD src1_sel:WORD_0
	v_lshl_add_u32 v5, v1, 10, v2
	v_and_b32_e32 v20, 0xffffffe0, v1
	v_lshlrev_b32_e32 v6, 1, v1
	v_lshrrev_b32_e32 v1, 2, v1
	v_and_b32_e32 v26, 3, v16
	v_lshl_add_u32 v130, v4, 10, v3
	v_and_b32_e32 v22, 24, v6
	v_and_b32_e32 v23, 4, v1
	v_or_b32_e32 v1, v20, v26
	v_and_b32_e32 v21, 0xffffffe0, v4
	v_lshlrev_b32_e32 v6, 1, v4
	v_lshrrev_b32_e32 v4, 2, v4
	v_and_b32_e32 v28, 3, v25
	v_or3_b32 v1, v1, v22, v23
	v_and_b32_e32 v24, 24, v6
	v_and_b32_e32 v27, 4, v4
	v_or_b32_e32 v4, v21, v28
	v_add_u32_e32 v149, 0, v0
	v_or3_b32 v4, v4, v24, v27
	v_lshl_add_u32 v64, v1, 9, v2
	v_add_u32_e32 v150, 0x10000, v149
	v_lshl_add_u32 v2, v4, 9, v3
	v_lshlrev_b64 v[8:9], 1, v[64:65]
	v_readfirstlane_b32 s2, v150
	v_mov_b32_e32 v3, v65
	v_add_u32_e32 v152, 0x12000, v149
	v_mov_b32_e32 v64, v5
	v_lshl_add_u64 v[0:1], s[22:23], 0, v[8:9]
	s_mov_b32 m0, s2
	v_lshlrev_b64 v[30:31], 1, v[2:3]
	v_readfirstlane_b32 s2, v152
	v_lshlrev_b64 v[32:33], 1, v[64:65]
	global_load_lds_dwordx4 v[0:1], off
	v_lshl_add_u64 v[2:3], s[22:23], 0, v[30:31]
	s_mov_b32 m0, s2
	v_lshl_add_u64 v[4:5], s[44:45], 0, v[32:33]
	s_mov_b64 s[22:23], 0x400
	v_readfirstlane_b32 s2, v149
	global_load_lds_dwordx4 v[2:3], off
	v_lshl_add_u64 v[6:7], v[4:5], 0, s[22:23]
	s_mov_b32 m0, s2
	v_lshlrev_b64 v[34:35], 1, v[130:131]
	v_add_u32_e32 v153, 0x2000, v149
	global_load_lds_dwordx4 v[6:7], off
	v_lshl_add_u64 v[6:7], s[44:45], 0, v[34:35]
	v_readfirstlane_b32 s2, v153
	v_add_u32_e32 v154, 0x14000, v149
	v_lshl_add_u64 v[10:11], v[6:7], 0, s[22:23]
	s_mov_b32 m0, s2
	v_readfirstlane_b32 s2, v154
	v_add_u32_e32 v156, 0x16000, v149
	global_load_lds_dwordx4 v[10:11], off
	v_lshl_add_u64 v[10:11], s[8:9], 0, v[8:9]
	s_mov_b32 m0, s2
	v_readfirstlane_b32 s2, v156
	global_load_lds_dwordx4 v[10:11], off
	s_mov_b32 m0, s2
	s_add_u32 s2, s44, 0x40400
	v_add_u32_e32 v157, 0x4000, v149
	v_lshl_add_u64 v[8:9], s[8:9], 0, v[30:31]
	s_addc_u32 s3, s45, 0
	v_readfirstlane_b32 s7, v157
	global_load_lds_dwordx4 v[8:9], off
	v_lshl_add_u64 v[30:31], s[2:3], 0, v[32:33]
	s_mov_b32 m0, s7
	v_add_u32_e32 v158, 0x6000, v149
	global_load_lds_dwordx4 v[30:31], off
	v_lshl_add_u64 v[30:31], s[2:3], 0, v[34:35]
	v_readfirstlane_b32 s2, v158
	s_mov_b32 m0, s2
	v_ashrrev_i32_e32 v13, 8, v140
	global_load_lds_dwordx4 v[30:31], off
	v_cmp_eq_u32_e32 vcc, 1, v13
	s_and_saveexec_b64 s[8:9], vcc
	s_cbranch_execz .LBB0_990
	s_barrier

; DI unsigned pk_f16(float lo, float hi) { f32x2_t v = {lo, hi}; return __builtin_bit_cast(unsigned, __builtin_convertvector(v, f16x2_t)); }
; #define EPI_FOR _Pragma("unroll") for (int m = 0; m < 8; ++m) _Pragma("unroll") for (int n = 0; n < 4; ++n)
; DI void p10_phase(const Params& p, int layer, u16* dst, char* lds) {
;     ...
;     gemm256((const u16*)(ws + OFF_PB) + (size_t)row0 * PLE, PLE, (const u16*)(ws + OFF_WPE) + (size_t)col0 * PLE, (const u16*)(ws + OFF_WPE) + (size_t)(col0 + 128) * PLE, PLE, 4, acc, lds);
;     EPI_IDX_N
;     EPI_FOR {
;       u32x2 o; o[0] = pk_f16(ACC(m, n)[0], ACC(m, n)[1]); o[1] = pk_f16(ACC(m, n)[2], ACC(m, n)[3]);
;       tp[(m * 4 + n) * 512 + tid] = o;
;     }
.LBB0_1257:
	s_or_b64 exec, exec, s[22:23]
	s_waitcnt vmcnt(0)
	s_barrier
	s_getreg_b32 s2, hwreg(HW_REG_HW_ID, 0, 6)
	s_lshl_b32 s2, s2, 2
	s_and_b32 s2, s2, 0xfc
	s_add_i32 s2, s2, 0x20040
	v_mov_b32_e32 v64, s2
	ds_read_b32 v64, v64
	v_cvt_pk_f16_f32 v130, v122, v123
	v_cvt_pk_f16_f32 v48, v48, v49
	v_cvt_pk_f16_f32 v49, v50, v51
	v_cvt_pk_f16_f32 v114, v114, v115
	s_waitcnt lgkmcnt(0)
	v_readfirstlane_b32 s2, v64
	v_cvt_pk_f16_f32 v115, v116, v117
	v_cvt_pk_f16_f32 v98, v98, v99
	v_lshl_or_b32 v122, s2, 6, v214
	v_cvt_pk_f16_f32 v99, v100, v101
	v_add_u32_e32 v50, 0x1a00, v122
	v_ashrrev_i32_e32 v51, 31, v50
	v_lshl_add_u64 v[50:51], v[50:51], 3, s[16:17]
	global_store_dwordx2 v[50:51], v[48:49], off sc0 sc1
	v_add_u32_e32 v50, 0x1c00, v122
	v_ashrrev_i32_e32 v51, 31, v50
	v_cvt_pk_f16_f32 v48, v78, v79
	v_cvt_pk_f16_f32 v49, v80, v81
	v_lshl_add_u64 v[50:51], v[50:51], 3, s[16:17]
	global_store_dwordx2 v[50:51], v[48:49], off sc0 sc1
	v_add_u32_e32 v50, 0x1e00, v122
	v_ashrrev_i32_e32 v51, 31, v50
	v_cvt_pk_f16_f32 v48, v60, v61
	v_cvt_pk_f16_f32 v49, v62, v63
	v_lshl_add_u64 v[50:51], v[50:51], 3, s[16:17]
	global_store_dwordx2 v[50:51], v[48:49], off sc0 sc1
	v_add_u32_e32 v48, 0x2000, v122
	v_ashrrev_i32_e32 v49, 31, v48
	v_cvt_pk_f16_f32 v50, v74, v75
	v_cvt_pk_f16_f32 v51, v76, v77
	v_lshl_add_u64 v[48:49], v[48:49], 3, s[16:17]
	v_add_u32_e32 v116, 0x200, v122
	v_add_u32_e32 v100, 0xa00, v122
	v_cvt_pk_f16_f32 v82, v82, v83
	v_cvt_pk_f16_f32 v83, v84, v85
	v_add_u32_e32 v84, 0x1200, v122
	global_store_dwordx2 v[48:49], v[50:51], off sc0 sc1
	v_add_u32_e32 v50, 0x2200, v122
	v_ashrrev_i32_e32 v117, 31, v116
	v_ashrrev_i32_e32 v101, 31, v100
	v_ashrrev_i32_e32 v85, 31, v84
	v_ashrrev_i32_e32 v51, 31, v50
	v_lshl_add_u64 v[116:117], v[116:117], 3, s[16:17]
	v_lshl_add_u64 v[100:101], v[100:101], 3, s[16:17]
	v_lshl_add_u64 v[84:85], v[84:85], 3, s[16:17]
	v_cvt_pk_f16_f32 v48, v56, v57
	v_cvt_pk_f16_f32 v49, v58, v59
	v_lshl_add_u64 v[50:51], v[50:51], 3, s[16:17]
	global_store_dwordx2 v[116:117], v[114:115], off sc0 sc1
	v_add_u32_e32 v116, 0x400, v122
	global_store_dwordx2 v[100:101], v[98:99], off sc0 sc1
	v_add_u32_e32 v100, 0xc00, v122
	global_store_dwordx2 v[84:85], v[82:83], off sc0 sc1
	v_add_u32_e32 v84, 0x1400, v122
	global_store_dwordx2 v[50:51], v[48:49], off sc0 sc1
	v_add_u32_e32 v50, 0x2400, v122
	v_ashrrev_i32_e32 v117, 31, v116
	v_ashrrev_i32_e32 v101, 31, v100
	v_ashrrev_i32_e32 v85, 31, v84
	v_ashrrev_i32_e32 v51, 31, v50
	v_cvt_pk_f16_f32 v114, v126, v127
	v_cvt_pk_f16_f32 v115, v128, v129
	v_lshl_add_u64 v[116:117], v[116:117], 3, s[16:17]
	v_cvt_pk_f16_f32 v98, v110, v111
	v_cvt_pk_f16_f32 v99, v112, v113
	v_lshl_add_u64 v[100:101], v[100:101], 3, s[16:17]
	v_cvt_pk_f16_f32 v82, v94, v95
	v_cvt_pk_f16_f32 v83, v96, v97
	v_lshl_add_u64 v[84:85], v[84:85], 3, s[16:17]
	v_cvt_pk_f16_f32 v48, v70, v71
	v_cvt_pk_f16_f32 v49, v72, v73
	v_lshl_add_u64 v[50:51], v[50:51], 3, s[16:17]
	global_store_dwordx2 v[116:117], v[114:115], off sc0 sc1
	v_add_u32_e32 v116, 0x600, v122
	global_store_dwordx2 v[100:101], v[98:99], off sc0 sc1
	v_add_u32_e32 v100, 0xe00, v122
	global_store_dwordx2 v[84:85], v[82:83], off sc0 sc1
	v_add_u32_e32 v84, 0x1600, v122
	global_store_dwordx2 v[50:51], v[48:49], off sc0 sc1
	v_add_u32_e32 v50, 0x2600, v122
	v_cvt_pk_f16_f32 v36, v36, v37
	v_cvt_pk_f16_f32 v37, v38, v39
	v_add_u32_e32 v38, 0x2a00, v122
	v_cvt_pk_f16_f32 v32, v32, v33
	v_cvt_pk_f16_f32 v33, v34, v35
	v_add_u32_e32 v34, 0x2e00, v122
	v_cvt_pk_f16_f32 v20, v20, v21
	v_cvt_pk_f16_f32 v21, v22, v23
	v_add_u32_e32 v22, 0x3200, v122
	v_cvt_pk_f16_f32 v16, v16, v17
	v_cvt_pk_f16_f32 v17, v18, v19
	v_add_u32_e32 v18, 0x3600, v122
	v_cvt_pk_f16_f32 v4, v4, v5
	v_cvt_pk_f16_f32 v5, v6, v7
	v_add_u32_e32 v6, 0x3a00, v122
	v_ashrrev_i32_e32 v117, 31, v116
	v_ashrrev_i32_e32 v101, 31, v100
	v_ashrrev_i32_e32 v85, 31, v84
	v_ashrrev_i32_e32 v51, 31, v50
	v_ashrrev_i32_e32 v39, 31, v38
	v_ashrrev_i32_e32 v35, 31, v34
	v_ashrrev_i32_e32 v23, 31, v22
	v_ashrrev_i32_e32 v19, 31, v18
	v_ashrrev_i32_e32 v7, 31, v6
	s_lshl_b64 s[22:23], s[36:37], 11
	v_readlane_b32 s28, v254, 12
	v_cvt_pk_f16_f32 v114, v118, v119
	v_cvt_pk_f16_f32 v115, v120, v121
	v_lshl_add_u64 v[116:117], v[116:117], 3, s[16:17]
	v_cvt_pk_f16_f32 v98, v102, v103
	v_cvt_pk_f16_f32 v99, v104, v105
	v_lshl_add_u64 v[100:101], v[100:101], 3, s[16:17]
	v_cvt_pk_f16_f32 v82, v86, v87
	v_cvt_pk_f16_f32 v83, v88, v89
	v_lshl_add_u64 v[84:85], v[84:85], 3, s[16:17]
	v_cvt_pk_f16_f32 v48, v52, v53
	v_cvt_pk_f16_f32 v49, v54, v55
	v_lshl_add_u64 v[50:51], v[50:51], 3, s[16:17]
	v_lshl_add_u64 v[38:39], v[38:39], 3, s[16:17]
	v_lshl_add_u64 v[34:35], v[34:35], 3, s[16:17]
	v_lshl_add_u64 v[22:23], v[22:23], 3, s[16:17]
	v_lshl_add_u64 v[18:19], v[18:19], 3, s[16:17]
	v_lshl_add_u64 v[6:7], v[6:7], 3, s[16:17]
	v_readlane_b32 s29, v254, 13
	s_add_u32 s22, s28, s22
	global_store_dwordx2 v[116:117], v[114:115], off sc0 sc1
	v_add_u32_e32 v114, 0x800, v122
	global_store_dwordx2 v[100:101], v[98:99], off sc0 sc1
	v_add_u32_e32 v98, 0x1000, v122
	global_store_dwordx2 v[84:85], v[82:83], off sc0 sc1
	v_add_u32_e32 v82, 0x1800, v122
	global_store_dwordx2 v[50:51], v[48:49], off sc0 sc1
	v_add_u32_e32 v48, 0x2800, v122
	global_store_dwordx2 v[38:39], v[36:37], off sc0 sc1
	v_add_u32_e32 v38, 0x2c00, v122
	global_store_dwordx2 v[34:35], v[32:33], off sc0 sc1
	v_add_u32_e32 v32, 0x3000, v122
	global_store_dwordx2 v[22:23], v[20:21], off sc0 sc1
	v_add_u32_e32 v22, 0x3400, v122
	global_store_dwordx2 v[18:19], v[16:17], off sc0 sc1
	v_add_u32_e32 v16, 0x3800, v122
	global_store_dwordx2 v[6:7], v[4:5], off sc0 sc1
; DI unsigned pk_f16(float lo, float hi) { f32x2_t v = {lo, hi}; return __builtin_bit_cast(unsigned, __builtin_convertvector(v, f16x2_t)); }
; DI int my_tid() { int t = tid_raw(); asm volatile("" : "+v"(t)); return t; }
; #define STAGE_A(b, h, kt) { const u16* ap_ = A + (size_t)((h) * ahalf + (unsigned)(kt) * 64u); glds16(ap_ + ao0, l0 + SA_(b, h)); glds16(ap_ + ao1, l0 + SA_(b, h) + 8192); }
; #define STAGE_B(b, h, kt) { const u16* bp_ = ((h) ? B1 : B0) + (unsigned)(kt) * 64u; glds16(bp_ + bo0, l0 + SB_(b, h)); glds16(bp_ + bo1, l0 + SB_(b, h) + 8192); }
; #define WAIT_V(n) asm volatile("s_waitcnt vmcnt(" #n ")" ::: "memory");
; #define BAR __builtin_amdgcn_s_barrier();
; #define EPI_FOR _Pragma("unroll") for (int m = 0; m < 8; ++m) _Pragma("unroll") for (int n = 0; n < 4; ++n)
; DI void gemm256(const u16* __restrict__ A, int lda, const u16* __restrict__ B0, const u16* __restrict__ B1, int ldb, int nt, acc_t& acc, char* lds) {
;   const int tid = my_tid();
;   const int lane = tid & 63, wid = tid >> 6, wr = wid >> 2, wc = wid & 3, fr = lane & 15, fq = lane >> 4;
;   int r0, c0, r1, c1;
;   stage_rc(tid * 16, r0, c0); stage_rc(tid * 16 + 8192, r1, c1);
;   const unsigned ao0 = (unsigned)(r0 * lda + c0), ao1 = (unsigned)(r1 * lda + c1);
;   const unsigned ahalf = 128u * (unsigned)lda;
;   const int p0 = (r0 & ~31) + (((r0 & 15) >> 2) * 8) + (((r0 >> 4) & 1) * 4) + (r0 & 3), p1 = (r1 & ~31) + (((r1 & 15) >> 2) * 8) + (((r1 >> 4) & 1) * 4) + (r1 & 3);
;   const unsigned bo0 = (unsigned)(p0 * ldb + c0), bo1 = (unsigned)(p1 * ldb + c1);
;   char* l0 = lds + tid * 16;
;     ...
;   bf16x8 At[4][2], Bq0[2][2], Bq1[2][2];
;   WAIT_V(0)
;   STAGE_B(0, 0, 0) STAGE_A(0, 0, 0) STAGE_B(0, 1, 0) STAGE_A(0, 1, 0)
;   if (wr == 1) BAR
; DI void p10_phase(const Params& p, int layer, u16* dst, char* lds) {
;     ...
;     EPI_FOR {
;       u32x2 o; o[0] = pk_f16(ACC(m, n)[0], ACC(m, n)[1]); o[1] = pk_f16(ACC(m, n)[2], ACC(m, n)[3]);
;       tp[(m * 4 + n) * 512 + tid] = o;
;     }
	v_add_u32_e32 v6, 0x3c00, v122
	v_cvt_pk_f16_f32 v0, v0, v1
	v_cvt_pk_f16_f32 v1, v2, v3
	v_add_u32_e32 v2, 0x3e00, v122
	s_addc_u32 s23, s29, s23
	s_lshl_b64 s[28:29], s[42:43], 11
	v_readlane_b32 s54, v252, 34
	v_ashrrev_i32_e32 v123, 31, v122
	v_ashrrev_i32_e32 v115, 31, v114
	v_ashrrev_i32_e32 v99, 31, v98
	v_ashrrev_i32_e32 v83, 31, v82
	v_ashrrev_i32_e32 v49, 31, v48
	v_ashrrev_i32_e32 v39, 31, v38
	v_ashrrev_i32_e32 v33, 31, v32
	v_ashrrev_i32_e32 v23, 31, v22
	v_ashrrev_i32_e32 v17, 31, v16
	v_ashrrev_i32_e32 v7, 31, v6
	v_ashrrev_i32_e32 v3, 31, v2
	v_readlane_b32 s55, v252, 35
	s_add_u32 s46, s54, s28
	v_cvt_pk_f16_f32 v131, v124, v125
	v_lshl_add_u64 v[124:125], v[122:123], 3, s[16:17]
	v_cvt_pk_f16_f32 v106, v106, v107
	v_cvt_pk_f16_f32 v107, v108, v109
	v_lshl_add_u64 v[108:109], v[114:115], 3, s[16:17]
	v_cvt_pk_f16_f32 v90, v90, v91
	v_cvt_pk_f16_f32 v91, v92, v93
	v_lshl_add_u64 v[92:93], v[98:99], 3, s[16:17]
	v_cvt_pk_f16_f32 v66, v66, v67
	v_cvt_pk_f16_f32 v67, v68, v69
	v_lshl_add_u64 v[68:69], v[82:83], 3, s[16:17]
	v_cvt_pk_f16_f32 v44, v44, v45
	v_cvt_pk_f16_f32 v45, v46, v47
	v_lshl_add_u64 v[46:47], v[48:49], 3, s[16:17]
	v_cvt_pk_f16_f32 v36, v40, v41
	v_cvt_pk_f16_f32 v37, v42, v43
	v_lshl_add_u64 v[38:39], v[38:39], 3, s[16:17]
	v_cvt_pk_f16_f32 v28, v28, v29
	v_cvt_pk_f16_f32 v29, v30, v31
	v_lshl_add_u64 v[30:31], v[32:33], 3, s[16:17]
	v_cvt_pk_f16_f32 v20, v24, v25
	v_cvt_pk_f16_f32 v21, v26, v27
	v_lshl_add_u64 v[22:23], v[22:23], 3, s[16:17]
	v_cvt_pk_f16_f32 v12, v12, v13
	v_cvt_pk_f16_f32 v13, v14, v15
	v_lshl_add_u64 v[14:15], v[16:17], 3, s[16:17]
	v_cvt_pk_f16_f32 v4, v8, v9
	v_cvt_pk_f16_f32 v5, v10, v11
	v_lshl_add_u64 v[6:7], v[6:7], 3, s[16:17]
	v_lshl_add_u64 v[2:3], v[2:3], 3, s[16:17]
	s_addc_u32 s47, s55, s29
	s_lshl_b64 s[44:45], s[8:9], 11
	global_store_dwordx2 v[124:125], v[130:131], off sc0 sc1
	global_store_dwordx2 v[108:109], v[106:107], off sc0 sc1
	global_store_dwordx2 v[92:93], v[90:91], off sc0 sc1
	global_store_dwordx2 v[68:69], v[66:67], off sc0 sc1
	global_store_dwordx2 v[46:47], v[44:45], off sc0 sc1
	global_store_dwordx2 v[38:39], v[36:37], off sc0 sc1
	global_store_dwordx2 v[30:31], v[28:29], off sc0 sc1
	global_store_dwordx2 v[22:23], v[20:21], off sc0 sc1
	global_store_dwordx2 v[14:15], v[12:13], off sc0 sc1
	global_store_dwordx2 v[6:7], v[4:5], off sc0 sc1
	global_store_dwordx2 v[2:3], v[0:1], off sc0 sc1
	s_add_u32 s44, s54, s44
	s_getreg_b32 s2, hwreg(HW_REG_HW_ID, 0, 6)
	s_addc_u32 s45, s55, s45
	s_lshl_b32 s2, s2, 2
	s_and_b32 s2, s2, 0xfc
	s_add_i32 s2, s2, 0x20040
	v_mov_b32_e32 v0, s2
	ds_read_b32 v0, v0
	v_mov_b32_e32 v131, v65
	s_waitcnt lgkmcnt(0)
	v_readfirstlane_b32 s2, v0
	s_nop 1
	v_lshl_or_b32 v146, s2, 6, v214
	s_nop 0
	v_bfe_i32 v2, v146, 27, 1
	v_lshlrev_b32_e32 v0, 4, v146
	v_lshrrev_b32_e32 v2, 22, v2
	v_add_u32_e32 v2, v0, v2
	v_and_b32_e32 v2, 0xfffffc00, v2
	v_sub_u32_e32 v2, v0, v2
	v_ashrrev_i32_e32 v1, 31, v146
	v_lshrrev_b32_e32 v3, 4, v2
	v_lshrrev_b32_e32 v1, 26, v1
	v_bitop3_b32 v3, v3, v2, 32 bitop3:0x6c
	v_ashrrev_i32_e32 v2, 31, v2
	v_add_u32_e32 v1, v146, v1
	v_lshrrev_b32_e32 v2, 26, v2
	v_ashrrev_i32_e32 v1, 6, v1
	v_add_u32_e32 v2, v3, v2
	v_lshlrev_b32_e32 v4, 3, v1
	v_ashrrev_i32_e32 v2, 6, v2
	v_lshlrev_b32_e32 v1, 5, v1
	v_and_b32_e32 v16, 32, v1
	v_mul_i32_i24_e32 v1, 64, v2
	v_sub_u32_e32 v1, v3, v1
	v_add_u32_e32 v3, 0x2000, v0
	v_ashrrev_i32_e32 v5, 31, v3
	v_lshrrev_b32_e32 v5, 22, v5
	v_add_u32_e32 v5, v3, v5
	v_ashrrev_i32_e32 v12, 10, v5
	v_mul_i32_i24_e32 v5, 0x400, v12
	v_sub_u32_e32 v3, v3, v5
	v_lshrrev_b32_e32 v5, 4, v3
	v_bitop3_b32 v3, v5, v3, 32 bitop3:0x6c
	v_ashrrev_i32_e32 v6, 31, v3
	v_lshrrev_b32_e32 v6, 26, v6
	v_and_b32_e32 v4, -16, v4
	v_ashrrev_i16_sdwa v17, v215, sext(v1) dst_sel:DWORD dst_unused:UNUSED_PAD src0_sel:DWORD src1_sel:BYTE_0
	v_lshlrev_b32_e32 v5, 3, v12
	v_add_u32_e32 v6, v3, v6
	v_add_u32_e32 v4, v2, v4
	v_add_u32_sdwa v1, v16, sext(v17) dst_sel:DWORD dst_unused:UNUSED_PAD src0_sel:DWORD src1_sel:WORD_0
	v_and_b32_e32 v5, -16, v5
	v_ashrrev_i32_e32 v13, 6, v6
	v_and_b32_e32 v6, 0xc0, v6
	v_add_u32_e32 v5, v13, v5
	v_sub_u32_e32 v3, v3, v6
	v_lshl_add_u32 v8, v4, 10, v1
	v_and_b32_e32 v18, 0xffffffe0, v4
	v_lshlrev_b32_e32 v6, 1, v4
	v_lshrrev_b32_e32 v4, 2, v4
	v_and_b32_e32 v21, 4, v4
	v_and_b32_e32 v23, 3, v2
	v_lshlrev_b32_e32 v4, 1, v5
	v_lshlrev_b32_e32 v7, 5, v12
	v_and_b32_e32 v20, 24, v6
	v_or_b32_e32 v2, v18, v23
	v_and_b32_e32 v19, 0xffffffe0, v5
	v_and_b32_e32 v22, 24, v4
	v_lshrrev_b32_e32 v4, 2, v5
	v_and_b32_e32 v25, 3, v13
	v_and_b32_e32 v14, 32, v7
	v_ashrrev_i16_sdwa v15, v215, sext(v3) dst_sel:DWORD dst_unused:UNUSED_PAD src0_sel:DWORD src1_sel:BYTE_0
	v_or3_b32 v2, v2, v20, v21
	v_and_b32_e32 v24, 4, v4
	v_or_b32_e32 v4, v19, v25
	v_add_u32_e32 v140, 0, v0
	v_add_u32_sdwa v3, v14, sext(v15) dst_sel:DWORD dst_unused:UNUSED_PAD src0_sel:DWORD src1_sel:WORD_0
	v_or3_b32 v4, v4, v22, v24
	v_lshl_add_u32 v64, v2, 10, v1
	v_add_u32_e32 v141, 0x10000, v140
	v_lshl_add_u32 v130, v5, 10, v3
	v_lshl_add_u32 v2, v4, 10, v3
	v_lshlrev_b64 v[6:7], 1, v[64:65]
	v_readfirstlane_b32 s2, v141
	v_mov_b32_e32 v3, v65
	v_add_u32_e32 v152, 0x12000, v140
	v_lshl_add_u64 v[0:1], s[46:47], 0, v[6:7]
	s_mov_b32 m0, s2
	v_lshlrev_b64 v[26:27], 1, v[2:3]
	v_readfirstlane_b32 s2, v152
	v_mov_b32_e32 v64, v8
	global_load_lds_dwordx4 v[0:1], off
	v_lshl_add_u64 v[2:3], s[46:47], 0, v[26:27]
	s_mov_b32 m0, s2
	v_lshlrev_b64 v[28:29], 1, v[64:65]
	v_readfirstlane_b32 s2, v140
	v_add_u32_e32 v153, 0x2000, v140
	global_load_lds_dwordx4 v[2:3], off
	v_lshl_add_u64 v[4:5], s[22:23], 0, v[28:29]
	s_mov_b32 m0, s2
	v_lshlrev_b64 v[30:31], 1, v[130:131]
	v_readfirstlane_b32 s2, v153
	v_add_u32_e32 v154, 0x14000, v140
	global_load_lds_dwordx4 v[4:5], off
	v_lshl_add_u64 v[8:9], s[22:23], 0, v[30:31]
	s_mov_b32 m0, s2
	v_readfirstlane_b32 s2, v154
	v_add_u32_e32 v155, 0x16000, v140
	global_load_lds_dwordx4 v[8:9], off
	v_lshl_add_u64 v[10:11], s[44:45], 0, v[6:7]
	s_mov_b32 m0, s2
	v_lshl_add_u64 v[6:7], s[44:45], 0, v[26:27]
	v_readfirstlane_b32 s2, v155
	s_add_u32 s44, s22, 0x40000
	v_add_u32_e32 v157, 0x4000, v140
	global_load_lds_dwordx4 v[10:11], off
	s_mov_b32 m0, s2
	s_addc_u32 s45, s23, 0
	v_readfirstlane_b32 s2, v157
	v_add_u32_e32 v158, 0x6000, v140
	global_load_lds_dwordx4 v[6:7], off
	v_lshl_add_u64 v[26:27], s[44:45], 0, v[28:29]
	s_mov_b32 m0, s2
	v_readfirstlane_b32 s2, v158
	global_load_lds_dwordx4 v[26:27], off
	v_lshl_add_u64 v[26:27], s[44:45], 0, v[30:31]
	s_mov_b32 m0, s2
	s_nop 0
	global_load_lds_dwordx4 v[26:27], off
	v_ashrrev_i32_e32 v26, 8, v146
	v_cmp_eq_u32_e32 vcc, 1, v26
	s_and_saveexec_b64 s[44:45], vcc
	s_cbranch_execz .LBB0_1259
	s_barrier
